# stack11: up-projection epilogue folds the bias add into the first conv tap (64 fewer packed ops per tile per wave) on top of stack10
# speedup vs baseline: 1.0065x; 1.0034x over previous
; __device__ __forceinline__ unsigned cvt_pk_bf16(float lo, float hi) { unsigned r; asm volatile("v_cvt_pk_bf16_f32 %0, %1, %2" : "=v"(r) : "v"(lo), "v"(hi)); return r; }
; DI float dpp_ror1(float x) { float r; asm volatile("s_nop 1\n\tv_mov_b32_dpp %0, %1 row_ror:1 row_mask:0xf bank_mask:0xf" : "=v"(r) : "v"(x)); return r; }
; DI float dpp_ror2(float x) { float r; asm volatile("s_nop 1\n\tv_mov_b32_dpp %0, %1 row_ror:2 row_mask:0xf bank_mask:0xf" : "=v"(r) : "v"(x)); return r; }
;     __device__ __forceinline__ void operator()(const f32x4 (&acc)[2][2][4][2], const Unit& u, int wr, int wc, int fr_in, int fq_in) const {
;     ...
;                 for (int m = 0; m < 4; ++m) {
;                     f32x4 uu[2];
; #pragma unroll
;                     for (int bj = 0; bj < 2; ++bj) {
;                         const f32x4 cur = acc[ai][bj][m][n];
;                         f32x4 r1, r2;
; #pragma unroll
;                         for (int j = 0; j < 4; ++j) { r1[j] = dpp_ror1(cur[j]); r2[j] = dpp_ror2(cur[j]); }
;                         const f32x4 p1 = (fr >= 1) ? r1 : r1p[bj], p2 = (fr >= 2) ? r2 : r2p[bj];
;                         uu[bj] = w0[bj] * p2 + w1[bj] * p1 + w2[bj] * cur + bb[bj];
;                         r1p[bj] = r1; r2p[bj] = r2;
;                     }
;                     const int row = row0 + ai * HALF + m * 16;
;                     float a[4];
; #pragma unroll
;                     for (int j = 0; j < 4; ++j) { const float g = uu[0][j]; a[j] = g * __builtin_amdgcn_rcpf(1.f + __expf(-g)) * uu[1][j]; }
;                     u32x2 w; w.x = cvt_pk_bf16(a[0], a[1]); w.y = cvt_pk_bf16(a[2], a[3]);
;                     *(u32x2*)(ACT + (size_t)row * FFN + u.pn * HALF + wc * 32 + 8 * fq + 4 * n) = w;
.LBB0_720:
	s_or_b64 exec, exec, s[42:43]
	v_cmp_eq_u32_e32 vcc, 0, v217
	v_cmp_lt_u32_e64 s[42:43], 1, v217
	v_mov_b32_dpp v223, v126 row_ror:1 row_mask:0xf bank_mask:0xf
	v_mov_b32_dpp v224, v126 row_ror:2 row_mask:0xf bank_mask:0xf
	v_mov_b32_dpp v225, v127 row_ror:1 row_mask:0xf bank_mask:0xf
	v_mov_b32_dpp v226, v127 row_ror:2 row_mask:0xf bank_mask:0xf
	s_waitcnt lgkmcnt(0)
	v_cndmask_b32_e32 v175, v167, v175, vcc
	v_cndmask_b32_e32 v218, v166, v174, vcc
	v_cndmask_b32_e32 v177, v169, v177, vcc
	v_cndmask_b32_e32 v176, v168, v176, vcc
	v_cndmask_b32_e32 v221, v165, v173, vcc
	v_cndmask_b32_e32 v222, v164, v172, vcc
	v_cndmask_b32_e64 v172, v218, v224, s[42:43]
	v_cndmask_b32_e64 v173, v175, v226, s[42:43]
	s_lshl_b32 s2, s50, 8
	v_cndmask_b32_e32 v219, v163, v171, vcc
	v_cndmask_b32_e32 v220, v162, v170, vcc
	v_mov_b32_dpp v227, v128 row_ror:1 row_mask:0xf bank_mask:0xf
	v_mov_b32_dpp v228, v128 row_ror:2 row_mask:0xf bank_mask:0xf
	v_mov_b32_dpp v229, v129 row_ror:1 row_mask:0xf bank_mask:0xf
	v_mov_b32_dpp v230, v129 row_ror:2 row_mask:0xf bank_mask:0xf
	v_cndmask_b32_e32 v166, v223, v166, vcc
	v_cndmask_b32_e32 v167, v225, v167, vcc
	v_cndmask_b32_e64 v170, v176, v228, s[42:43]
	v_cndmask_b32_e64 v171, v177, v230, s[42:43]
	v_pk_fma_f32 v[172:173], v[150:151], v[172:173], v[134:135]
	s_add_i32 s2, s2, s67
	v_cndmask_b32_e32 v168, v227, v168, vcc
	v_cndmask_b32_e32 v169, v229, v169, vcc
	v_pk_fma_f32 v[170:171], v[152:153], v[170:171], v[136:137]
	v_pk_fma_f32 v[166:167], v[146:147], v[166:167], v[172:173]
	v_or_b32_e32 v174, s2, v217
	v_pk_fma_f32 v[168:169], v[148:149], v[168:169], v[170:171]
	v_pk_fma_f32 v[126:127], v[126:127], v[138:139], v[166:167]
	v_mov_b32_dpp v170, v122 row_ror:1 row_mask:0xf bank_mask:0xf
	v_mov_b32_dpp v171, v122 row_ror:2 row_mask:0xf bank_mask:0xf
	v_mov_b32_dpp v172, v123 row_ror:1 row_mask:0xf bank_mask:0xf
	v_mov_b32_dpp v173, v123 row_ror:2 row_mask:0xf bank_mask:0xf
	v_mov_b32_dpp v175, v124 row_ror:1 row_mask:0xf bank_mask:0xf
	v_mov_b32_dpp v176, v124 row_ror:2 row_mask:0xf bank_mask:0xf
	v_mov_b32_dpp v177, v125 row_ror:1 row_mask:0xf bank_mask:0xf
	v_mov_b32_dpp v217, v125 row_ror:2 row_mask:0xf bank_mask:0xf
	s_nop 0
	v_cndmask_b32_e64 v166, v222, v176, s[42:43]
	v_cndmask_b32_e64 v167, v221, v217, s[42:43]
	v_cndmask_b32_e32 v164, v175, v164, vcc
	v_cndmask_b32_e32 v165, v177, v165, vcc
	v_pk_fma_f32 v[166:167], v[160:161], v[166:167], v[132:133]
	v_pk_fma_f32 v[128:129], v[128:129], v[140:141], v[168:169]
	v_pk_fma_f32 v[164:165], v[156:157], v[164:165], v[166:167]
	v_mul_f32_e32 v166, 0xbfb8aa3b, v126
	v_exp_f32_e32 v166, v166
	v_cndmask_b32_e64 v168, v220, v171, s[42:43]
	v_cndmask_b32_e64 v169, v219, v173, s[42:43]
	v_cndmask_b32_e32 v162, v170, v162, vcc
	v_cndmask_b32_e32 v163, v172, v163, vcc
	v_pk_fma_f32 v[168:169], v[158:159], v[168:169], v[130:131]
	v_pk_fma_f32 v[162:163], v[154:155], v[162:163], v[168:169]
	v_pk_fma_f32 v[124:125], v[124:125], v[144:145], v[164:165]
	v_pk_fma_f32 v[122:123], v[122:123], v[142:143], v[162:163]
	v_add_f32_e32 v162, 1.0, v166
	v_rcp_f32_e32 v162, v162
	v_mul_f32_e32 v163, 0xbfb8aa3b, v127
	v_exp_f32_e32 v163, v163
	v_mul_f32_e32 v126, v126, v162
	v_mul_f32_e32 v122, v126, v122
	v_add_f32_e32 v126, 1.0, v163
	v_mul_f32_e32 v162, 0xbfb8aa3b, v128
	v_rcp_f32_e32 v126, v126
	v_exp_f32_e32 v162, v162
	v_mul_f32_e32 v163, 0xbfb8aa3b, v129
	v_exp_f32_e32 v163, v163
	v_mul_f32_e32 v126, v127, v126
	v_add_f32_e32 v127, 1.0, v162
	v_rcp_f32_e32 v127, v127
	v_add_f32_e32 v162, 1.0, v163
	v_rcp_f32_e32 v162, v162
	v_mul_f32_e32 v123, v126, v123
	v_mul_f32_e32 v126, v128, v127
	v_readlane_b32 s8, v240, 27
	s_lshl_b32 s46, s51, 7
	v_mul_f32_e32 v126, v126, v124
	v_mul_f32_e32 v124, v129, v162
	v_readlane_b32 s9, v240, 28
	s_ashr_i32 s47, s46, 31
	v_mul_f32_e32 v125, v124, v125
	v_cvt_pk_bf16_f32 v124, v122, v123
	v_mov_b64_e32 v[122:123], s[8:9]
	v_cvt_pk_bf16_f32 v125, v126, v125
	v_mad_i64_i32 v[126:127], s[22:23], v174, s25, v[122:123]
	s_lshl_b64 s[46:47], s[46:47], 1
	v_lshl_add_u64 v[126:127], v[126:127], 0, s[46:47]
	s_lshl_b32 s62, s31, 1
	v_lshl_add_u64 v[126:127], v[126:127], 0, s[62:63]
	v_lshlrev_b64 v[162:163], 1, v[200:201]
	v_lshl_add_u64 v[164:165], v[126:127], 0, v[162:163]
	global_store_dwordx2 v[164:165], v[124:125], off
	v_mov_b32_dpp v168, v118 row_ror:1 row_mask:0xf bank_mask:0xf
	v_mov_b32_dpp v169, v118 row_ror:2 row_mask:0xf bank_mask:0xf
	v_mov_b32_dpp v200, v119 row_ror:1 row_mask:0xf bank_mask:0xf
	v_mov_b32_dpp v201, v119 row_ror:2 row_mask:0xf bank_mask:0xf
	v_mov_b32_dpp v218, v120 row_ror:1 row_mask:0xf bank_mask:0xf
	v_mov_b32_dpp v219, v120 row_ror:2 row_mask:0xf bank_mask:0xf
	v_mov_b32_dpp v220, v121 row_ror:1 row_mask:0xf bank_mask:0xf
	s_nop 0
	v_cndmask_b32_e64 v166, v224, v169, s[42:43]
	v_cndmask_b32_e64 v167, v226, v201, s[42:43]
	v_mov_b32_dpp v221, v121 row_ror:2 row_mask:0xf bank_mask:0xf
	v_cndmask_b32_e32 v124, v168, v223, vcc
	v_cndmask_b32_e32 v125, v200, v225, vcc
	v_cndmask_b32_e64 v128, v228, v219, s[42:43]
	v_cndmask_b32_e64 v129, v230, v221, s[42:43]
	v_pk_fma_f32 v[166:167], v[150:151], v[166:167], v[134:135]
	v_cndmask_b32_e32 v126, v218, v227, vcc
	v_cndmask_b32_e32 v127, v220, v229, vcc
	v_pk_fma_f32 v[128:129], v[152:153], v[128:129], v[136:137]
	v_pk_fma_f32 v[124:125], v[146:147], v[124:125], v[166:167]
	v_pk_fma_f32 v[126:127], v[148:149], v[126:127], v[128:129]
	v_pk_fma_f32 v[118:119], v[118:119], v[138:139], v[124:125]
	v_mov_b32_dpp v222, v114 row_ror:1 row_mask:0xf bank_mask:0xf
	v_mov_b32_dpp v223, v114 row_ror:2 row_mask:0xf bank_mask:0xf
	v_mov_b32_dpp v224, v115 row_ror:1 row_mask:0xf bank_mask:0xf
; __device__ __forceinline__ unsigned cvt_pk_bf16(float lo, float hi) { unsigned r; asm volatile("v_cvt_pk_bf16_f32 %0, %1, %2" : "=v"(r) : "v"(lo), "v"(hi)); return r; }
; DI float dpp_ror1(float x) { float r; asm volatile("s_nop 1\n\tv_mov_b32_dpp %0, %1 row_ror:1 row_mask:0xf bank_mask:0xf" : "=v"(r) : "v"(x)); return r; }
; DI float dpp_ror2(float x) { float r; asm volatile("s_nop 1\n\tv_mov_b32_dpp %0, %1 row_ror:2 row_mask:0xf bank_mask:0xf" : "=v"(r) : "v"(x)); return r; }
;     __device__ __forceinline__ void operator()(const f32x4 (&acc)[2][2][4][2], const Unit& u, int wr, int wc, int fr_in, int fq_in) const {
;     ...
;                 for (int m = 0; m < 4; ++m) {
;                     f32x4 uu[2];
; #pragma unroll
;                     for (int bj = 0; bj < 2; ++bj) {
;                         const f32x4 cur = acc[ai][bj][m][n];
;                         f32x4 r1, r2;
; #pragma unroll
;                         for (int j = 0; j < 4; ++j) { r1[j] = dpp_ror1(cur[j]); r2[j] = dpp_ror2(cur[j]); }
;                         const f32x4 p1 = (fr >= 1) ? r1 : r1p[bj], p2 = (fr >= 2) ? r2 : r2p[bj];
;                         uu[bj] = w0[bj] * p2 + w1[bj] * p1 + w2[bj] * cur + bb[bj];
;                         r1p[bj] = r1; r2p[bj] = r2;
;                     }
;                     const int row = row0 + ai * HALF + m * 16;
;                     float a[4];
; #pragma unroll
;                     for (int j = 0; j < 4; ++j) { const float g = uu[0][j]; a[j] = g * __builtin_amdgcn_rcpf(1.f + __expf(-g)) * uu[1][j]; }
;                     u32x2 w; w.x = cvt_pk_bf16(a[0], a[1]); w.y = cvt_pk_bf16(a[2], a[3]);
;                     *(u32x2*)(ACT + (size_t)row * FFN + u.pn * HALF + wc * 32 + 8 * fq + 4 * n) = w;
	v_mov_b32_dpp v225, v115 row_ror:2 row_mask:0xf bank_mask:0xf
	v_mov_b32_dpp v226, v116 row_ror:1 row_mask:0xf bank_mask:0xf
	v_mov_b32_dpp v227, v116 row_ror:2 row_mask:0xf bank_mask:0xf
	v_mov_b32_dpp v228, v117 row_ror:1 row_mask:0xf bank_mask:0xf
	v_mov_b32_dpp v229, v117 row_ror:2 row_mask:0xf bank_mask:0xf
	v_pk_fma_f32 v[120:121], v[120:121], v[140:141], v[126:127]
	v_cndmask_b32_e64 v128, v176, v227, s[42:43]
	v_cndmask_b32_e64 v129, v217, v229, s[42:43]
	v_cndmask_b32_e32 v126, v226, v175, vcc
	v_cndmask_b32_e32 v127, v228, v177, vcc
	v_pk_fma_f32 v[128:129], v[160:161], v[128:129], v[132:133]
	v_cndmask_b32_e64 v166, v171, v223, s[42:43]
	v_pk_fma_f32 v[126:127], v[156:157], v[126:127], v[128:129]
	v_mul_f32_e32 v128, 0xbfb8aa3b, v118
	v_exp_f32_e32 v128, v128
	v_cndmask_b32_e64 v167, v173, v225, s[42:43]
	v_cndmask_b32_e32 v124, v222, v170, vcc
	v_cndmask_b32_e32 v125, v224, v172, vcc
	v_pk_fma_f32 v[166:167], v[158:159], v[166:167], v[130:131]
	v_pk_fma_f32 v[124:125], v[154:155], v[124:125], v[166:167]
	v_pk_fma_f32 v[116:117], v[116:117], v[144:145], v[126:127]
	v_pk_fma_f32 v[114:115], v[114:115], v[142:143], v[124:125]
	v_add_f32_e32 v124, 1.0, v128
	v_rcp_f32_e32 v124, v124
	v_mul_f32_e32 v125, 0xbfb8aa3b, v119
	v_exp_f32_e32 v125, v125
	v_mul_f32_e32 v118, v118, v124
	v_mul_f32_e32 v114, v118, v114
	v_add_f32_e32 v118, 1.0, v125
	v_mul_f32_e32 v124, 0xbfb8aa3b, v120
	v_rcp_f32_e32 v118, v118
	v_exp_f32_e32 v124, v124
	v_mul_f32_e32 v125, 0xbfb8aa3b, v121
	v_exp_f32_e32 v125, v125
	v_mul_f32_e32 v118, v119, v118
	v_add_f32_e32 v119, 1.0, v124
	v_rcp_f32_e32 v119, v119
	v_add_f32_e32 v124, 1.0, v125
	v_rcp_f32_e32 v124, v124
	v_mul_f32_e32 v115, v118, v115
	v_mul_f32_e32 v118, v120, v119
	v_mul_f32_e32 v116, v118, v116
	v_mul_f32_e32 v118, v121, v124
	v_mul_f32_e32 v117, v118, v117
	v_or_b32_e32 v118, 16, v174
	v_cvt_pk_bf16_f32 v114, v114, v115
	v_cvt_pk_bf16_f32 v115, v116, v117
	v_mad_i64_i32 v[116:117], s[22:23], v118, s25, v[122:123]
	v_lshl_add_u64 v[116:117], v[116:117], 0, s[46:47]
	v_lshl_add_u64 v[116:117], v[116:117], 0, s[62:63]
	v_lshl_add_u64 v[166:167], v[116:117], 0, v[162:163]
	global_store_dwordx2 v[166:167], v[114:115], off
	v_mov_b32_dpp v124, v110 row_ror:1 row_mask:0xf bank_mask:0xf
	v_mov_b32_dpp v125, v110 row_ror:2 row_mask:0xf bank_mask:0xf
	v_mov_b32_dpp v126, v111 row_ror:1 row_mask:0xf bank_mask:0xf
	v_mov_b32_dpp v127, v111 row_ror:2 row_mask:0xf bank_mask:0xf
	v_mov_b32_dpp v128, v112 row_ror:1 row_mask:0xf bank_mask:0xf
	v_mov_b32_dpp v129, v112 row_ror:2 row_mask:0xf bank_mask:0xf
	v_mov_b32_dpp v170, v113 row_ror:1 row_mask:0xf bank_mask:0xf
	s_nop 0
	v_cndmask_b32_e64 v120, v169, v125, s[42:43]
	v_cndmask_b32_e64 v121, v201, v127, s[42:43]
	v_mov_b32_dpp v171, v113 row_ror:2 row_mask:0xf bank_mask:0xf
	v_cndmask_b32_e32 v114, v124, v168, vcc
	v_cndmask_b32_e32 v115, v126, v200, vcc
	v_cndmask_b32_e64 v118, v219, v129, s[42:43]
	v_cndmask_b32_e64 v119, v221, v171, s[42:43]
	v_pk_fma_f32 v[120:121], v[150:151], v[120:121], v[134:135]
	v_cndmask_b32_e32 v116, v128, v218, vcc
	v_cndmask_b32_e32 v117, v170, v220, vcc
	v_pk_fma_f32 v[118:119], v[152:153], v[118:119], v[136:137]
	v_pk_fma_f32 v[114:115], v[146:147], v[114:115], v[120:121]
	v_pk_fma_f32 v[116:117], v[148:149], v[116:117], v[118:119]
	v_pk_fma_f32 v[110:111], v[110:111], v[138:139], v[114:115]
	v_mov_b32_dpp v172, v106 row_ror:1 row_mask:0xf bank_mask:0xf
	v_mov_b32_dpp v173, v106 row_ror:2 row_mask:0xf bank_mask:0xf
	v_mov_b32_dpp v175, v107 row_ror:1 row_mask:0xf bank_mask:0xf
	v_mov_b32_dpp v176, v107 row_ror:2 row_mask:0xf bank_mask:0xf
	v_mov_b32_dpp v177, v108 row_ror:1 row_mask:0xf bank_mask:0xf
	v_mov_b32_dpp v200, v108 row_ror:2 row_mask:0xf bank_mask:0xf
	v_mov_b32_dpp v201, v109 row_ror:1 row_mask:0xf bank_mask:0xf
	v_mov_b32_dpp v217, v109 row_ror:2 row_mask:0xf bank_mask:0xf
	v_pk_fma_f32 v[112:113], v[112:113], v[140:141], v[116:117]
	v_cndmask_b32_e64 v118, v227, v200, s[42:43]
	v_cndmask_b32_e64 v119, v229, v217, s[42:43]
	v_cndmask_b32_e32 v116, v177, v226, vcc
	v_cndmask_b32_e32 v117, v201, v228, vcc
	v_pk_fma_f32 v[118:119], v[160:161], v[118:119], v[132:133]
	v_cndmask_b32_e64 v120, v223, v173, s[42:43]
	v_pk_fma_f32 v[116:117], v[156:157], v[116:117], v[118:119]
	v_mul_f32_e32 v118, 0xbfb8aa3b, v110
	v_exp_f32_e32 v118, v118
	v_cndmask_b32_e64 v121, v225, v176, s[42:43]
	v_cndmask_b32_e32 v114, v172, v222, vcc
	v_cndmask_b32_e32 v115, v175, v224, vcc
	v_pk_fma_f32 v[120:121], v[158:159], v[120:121], v[130:131]
	v_pk_fma_f32 v[114:115], v[154:155], v[114:115], v[120:121]
	v_pk_fma_f32 v[108:109], v[108:109], v[144:145], v[116:117]
	v_pk_fma_f32 v[106:107], v[106:107], v[142:143], v[114:115]
	v_add_f32_e32 v114, 1.0, v118
	v_rcp_f32_e32 v114, v114
	v_mul_f32_e32 v115, 0xbfb8aa3b, v111
	v_exp_f32_e32 v115, v115
	v_mul_f32_e32 v110, v110, v114
	v_mul_f32_e32 v106, v110, v106
	v_add_f32_e32 v110, 1.0, v115
	v_mul_f32_e32 v114, 0xbfb8aa3b, v112
; __device__ __forceinline__ unsigned cvt_pk_bf16(float lo, float hi) { unsigned r; asm volatile("v_cvt_pk_bf16_f32 %0, %1, %2" : "=v"(r) : "v"(lo), "v"(hi)); return r; }
;     __device__ __forceinline__ void operator()(const f32x4 (&acc)[2][2][4][2], const Unit& u, int wr, int wc, int fr_in, int fq_in) const {
;     ...
;                 for (int bj = 0; bj < 2; ++bj) {
;                     const int tcol = bj * HALF + wc * 32 + 8 * fq + 4 * n;
;                     w0[bj] = *(const f32x4*)(cwl + eo + tcol); w1[bj] = *(const f32x4*)(cwl + eo + 256 + tcol); w2[bj] = *(const f32x4*)(cwl + eo + 512 + tcol); bb[bj] = *(const f32x4*)(cwl + eo + 768 + tcol);
;                     f32x4 E0 = (f32x4){0.f, 0.f, 0.f, 0.f}, E1 = E0;
;                     if (fr < 2) {
;                         if (wr == 1 || ai == 1) {
;                             const int sai = (wr == 1) ? ai : 0, swr = (wr == 1) ? 0 : 1;
;                             const int e = (((((sai * 2 + swr) * 4 + wc) * 2 + bj) * 2 + n) * 4 + fq) * 2;
;                             E0 = ex[e]; E1 = ex[e + 1];
;                         }
;                     }
;                     r1p[bj] = E1; r2p[bj] = (fr == 0) ? E0 : E1;
;     ...
;                 for (int m = 0; m < 4; ++m) {
;                     f32x4 uu[2];
; #pragma unroll
;                     for (int bj = 0; bj < 2; ++bj) {
;                         const f32x4 cur = acc[ai][bj][m][n];
;                         f32x4 r1, r2;
; #pragma unroll
;                         for (int j = 0; j < 4; ++j) { r1[j] = dpp_ror1(cur[j]); r2[j] = dpp_ror2(cur[j]); }
;                         const f32x4 p1 = (fr >= 1) ? r1 : r1p[bj], p2 = (fr >= 2) ? r2 : r2p[bj];
;                         uu[bj] = w0[bj] * p2 + w1[bj] * p1 + w2[bj] * cur + bb[bj];
;                         r1p[bj] = r1; r2p[bj] = r2;
;                     }
;                     const int row = row0 + ai * HALF + m * 16;
;                     float a[4];
; #pragma unroll
;                     for (int j = 0; j < 4; ++j) { const float g = uu[0][j]; a[j] = g * __builtin_amdgcn_rcpf(1.f + __expf(-g)) * uu[1][j]; }
;                     u32x2 w; w.x = cvt_pk_bf16(a[0], a[1]); w.y = cvt_pk_bf16(a[2], a[3]);
;                     *(u32x2*)(ACT + (size_t)row * FFN + u.pn * HALF + wc * 32 + 8 * fq + 4 * n) = w;
	v_rcp_f32_e32 v110, v110
	v_exp_f32_e32 v114, v114
	v_mul_f32_e32 v115, 0xbfb8aa3b, v113
	v_exp_f32_e32 v115, v115
	v_mul_f32_e32 v110, v111, v110
	v_add_f32_e32 v111, 1.0, v114
	v_rcp_f32_e32 v111, v111
	v_add_f32_e32 v114, 1.0, v115
	v_rcp_f32_e32 v114, v114
	v_mul_f32_e32 v107, v110, v107
	v_mul_f32_e32 v110, v112, v111
	v_mul_f32_e32 v108, v110, v108
	v_mul_f32_e32 v110, v113, v114
	v_mul_f32_e32 v109, v110, v109
	v_or_b32_e32 v110, 32, v174
	v_cvt_pk_bf16_f32 v106, v106, v107
	v_cvt_pk_bf16_f32 v107, v108, v109
	v_mad_i64_i32 v[108:109], s[22:23], v110, s25, v[122:123]
	v_lshl_add_u64 v[108:109], v[108:109], 0, s[46:47]
	v_lshl_add_u64 v[108:109], v[108:109], 0, s[62:63]
	v_lshl_add_u64 v[168:169], v[108:109], 0, v[162:163]
	global_store_dwordx2 v[168:169], v[106:107], off
	v_mov_b32_dpp v106, v102 row_ror:1 row_mask:0xf bank_mask:0xf
	v_mov_b32_dpp v112, v102 row_ror:2 row_mask:0xf bank_mask:0xf
	v_mov_b32_dpp v107, v103 row_ror:1 row_mask:0xf bank_mask:0xf
	v_mov_b32_dpp v113, v103 row_ror:2 row_mask:0xf bank_mask:0xf
	v_mov_b32_dpp v108, v104 row_ror:1 row_mask:0xf bank_mask:0xf
	v_mov_b32_dpp v110, v104 row_ror:2 row_mask:0xf bank_mask:0xf
	v_mov_b32_dpp v109, v105 row_ror:1 row_mask:0xf bank_mask:0xf
	v_mov_b32_dpp v111, v105 row_ror:2 row_mask:0xf bank_mask:0xf
	s_nop 0
	v_cndmask_b32_e64 v112, v125, v112, s[42:43]
	v_cndmask_b32_e64 v110, v129, v110, s[42:43]
	v_cndmask_b32_e64 v111, v171, v111, s[42:43]
	v_cndmask_b32_e64 v113, v127, v113, s[42:43]
	v_cndmask_b32_e32 v106, v106, v124, vcc
	v_cndmask_b32_e32 v107, v107, v126, vcc
	v_cndmask_b32_e32 v108, v108, v128, vcc
	v_cndmask_b32_e32 v109, v109, v170, vcc
	v_pk_fma_f32 v[112:113], v[150:151], v[112:113], v[134:135]
	v_pk_fma_f32 v[110:111], v[152:153], v[110:111], v[136:137]
	v_pk_fma_f32 v[106:107], v[146:147], v[106:107], v[112:113]
	v_pk_fma_f32 v[108:109], v[148:149], v[108:109], v[110:111]
	v_pk_fma_f32 v[102:103], v[102:103], v[138:139], v[106:107]
	v_pk_fma_f32 v[104:105], v[104:105], v[140:141], v[108:109]
	v_mov_b32_dpp v106, v98 row_ror:1 row_mask:0xf bank_mask:0xf
	v_mov_b32_dpp v112, v98 row_ror:2 row_mask:0xf bank_mask:0xf
	v_mov_b32_dpp v107, v99 row_ror:1 row_mask:0xf bank_mask:0xf
	v_mov_b32_dpp v113, v99 row_ror:2 row_mask:0xf bank_mask:0xf
	v_mov_b32_dpp v108, v100 row_ror:1 row_mask:0xf bank_mask:0xf
	v_mov_b32_dpp v110, v100 row_ror:2 row_mask:0xf bank_mask:0xf
	v_mov_b32_dpp v109, v101 row_ror:1 row_mask:0xf bank_mask:0xf
	v_mov_b32_dpp v111, v101 row_ror:2 row_mask:0xf bank_mask:0xf
	v_cndmask_b32_e64 v110, v200, v110, s[42:43]
	v_cndmask_b32_e64 v111, v217, v111, s[42:43]
	v_cndmask_b32_e32 v108, v108, v177, vcc
	v_cndmask_b32_e32 v109, v109, v201, vcc
	v_pk_fma_f32 v[110:111], v[160:161], v[110:111], v[132:133]
	v_cndmask_b32_e64 v112, v173, v112, s[42:43]
	v_pk_fma_f32 v[108:109], v[156:157], v[108:109], v[110:111]
	v_mul_f32_e32 v110, 0xbfb8aa3b, v102
	v_exp_f32_e32 v110, v110
	v_cndmask_b32_e64 v113, v176, v113, s[42:43]
	v_cndmask_b32_e32 v106, v106, v172, vcc
	v_cndmask_b32_e32 v107, v107, v175, vcc
	v_pk_fma_f32 v[112:113], v[158:159], v[112:113], v[130:131]
	v_pk_fma_f32 v[106:107], v[154:155], v[106:107], v[112:113]
	v_pk_fma_f32 v[100:101], v[100:101], v[144:145], v[108:109]
	v_pk_fma_f32 v[98:99], v[98:99], v[142:143], v[106:107]
	v_add_f32_e32 v106, 1.0, v110
	v_rcp_f32_e32 v106, v106
	v_mul_f32_e32 v107, 0xbfb8aa3b, v103
	v_exp_f32_e32 v107, v107
	v_mul_f32_e32 v102, v102, v106
	v_mul_f32_e32 v98, v102, v98
	v_add_f32_e32 v102, 1.0, v107
	v_mul_f32_e32 v106, 0xbfb8aa3b, v104
	v_rcp_f32_e32 v102, v102
	v_exp_f32_e32 v106, v106
	v_mul_f32_e32 v107, 0xbfb8aa3b, v105
	v_exp_f32_e32 v107, v107
	v_mul_f32_e32 v102, v103, v102
	v_add_f32_e32 v103, 1.0, v106
	v_rcp_f32_e32 v103, v103
	v_add_f32_e32 v106, 1.0, v107
	v_rcp_f32_e32 v106, v106
	v_mul_f32_e32 v99, v102, v99
	v_mul_f32_e32 v102, v104, v103
	v_mul_f32_e32 v100, v102, v100
	v_mul_f32_e32 v102, v105, v106
	v_mul_f32_e32 v101, v102, v101
	v_or_b32_e32 v102, 48, v174
	v_cvt_pk_bf16_f32 v98, v98, v99
	v_cvt_pk_bf16_f32 v99, v100, v101
	v_mad_i64_i32 v[100:101], s[22:23], v102, s25, v[122:123]
	v_lshl_add_u64 v[100:101], v[100:101], 0, s[46:47]
	v_lshl_add_u64 v[100:101], v[100:101], 0, s[62:63]
	v_lshl_add_u64 v[146:147], v[100:101], 0, v[162:163]
	global_store_dwordx2 v[146:147], v[98:99], off
	ds_read_b128 v[118:121], v214 offset:16
	ds_read_b128 v[114:117], v214 offset:1040
	ds_read_b128 v[106:109], v214 offset:2064
	ds_read_b128 v[102:105], v214 offset:3088
	v_add_u32_e32 v98, 4, v216
	v_mov_b32_e32 v138, 0
	v_lshlrev_b32_e32 v148, 5, v98
	v_mov_b32_e32 v142, 0
	v_mov_b32_e32 v143, 0
	v_mov_b32_e32 v144, 0
	v_mov_b32_e32 v145, 0
	v_mov_b32_e32 v134, 0
	v_mov_b32_e32 v135, 0
	v_mov_b32_e32 v136, 0
	v_mov_b32_e32 v137, 0
	s_and_saveexec_b64 s[50:51], s[48:49]
	s_cbranch_execz .LBB0_722
	s_lshl_b32 s2, s96, 4
	v_add3_u32 v98, v213, v148, s2
	ds_read_b128 v[142:145], v98
	ds_read_b128 v[134:137], v98 offset:16

; __device__ __forceinline__ unsigned cvt_pk_bf16(float lo, float hi) { unsigned r; asm volatile("v_cvt_pk_bf16_f32 %0, %1, %2" : "=v"(r) : "v"(lo), "v"(hi)); return r; }
; DI float dpp_ror1(float x) { float r; asm volatile("s_nop 1\n\tv_mov_b32_dpp %0, %1 row_ror:1 row_mask:0xf bank_mask:0xf" : "=v"(r) : "v"(x)); return r; }
; DI float dpp_ror2(float x) { float r; asm volatile("s_nop 1\n\tv_mov_b32_dpp %0, %1 row_ror:2 row_mask:0xf bank_mask:0xf" : "=v"(r) : "v"(x)); return r; }
;     __device__ __forceinline__ void operator()(const f32x4 (&acc)[2][2][4][2], const Unit& u, int wr, int wc, int fr_in, int fq_in) const {
;     ...
;                     r1p[bj] = E1; r2p[bj] = (fr == 0) ? E0 : E1;
;                 }
; #pragma unroll
;                 for (int m = 0; m < 4; ++m) {
;                     f32x4 uu[2];
; #pragma unroll
;                     for (int bj = 0; bj < 2; ++bj) {
;                         const f32x4 cur = acc[ai][bj][m][n];
;                         f32x4 r1, r2;
; #pragma unroll
;                         for (int j = 0; j < 4; ++j) { r1[j] = dpp_ror1(cur[j]); r2[j] = dpp_ror2(cur[j]); }
;                         const f32x4 p1 = (fr >= 1) ? r1 : r1p[bj], p2 = (fr >= 2) ? r2 : r2p[bj];
;                         uu[bj] = w0[bj] * p2 + w1[bj] * p1 + w2[bj] * cur + bb[bj];
;                         r1p[bj] = r1; r2p[bj] = r2;
;                     }
;                     const int row = row0 + ai * HALF + m * 16;
;                     float a[4];
; #pragma unroll
;                     for (int j = 0; j < 4; ++j) { const float g = uu[0][j]; a[j] = g * __builtin_amdgcn_rcpf(1.f + __expf(-g)) * uu[1][j]; }
;                     u32x2 w; w.x = cvt_pk_bf16(a[0], a[1]); w.y = cvt_pk_bf16(a[2], a[3]);
;                     *(u32x2*)(ACT + (size_t)row * FFN + u.pn * HALF + wc * 32 + 8 * fq + 4 * n) = w;
.LBB0_724:
	s_or_b64 exec, exec, s[50:51]
	s_waitcnt lgkmcnt(0)
	v_cndmask_b32_e32 v143, v135, v143, vcc
	v_cndmask_b32_e32 v142, v134, v142, vcc
	v_cndmask_b32_e32 v145, v137, v145, vcc
	v_cndmask_b32_e32 v144, v136, v144, vcc
	v_cndmask_b32_e32 v151, v133, v141, vcc
	v_cndmask_b32_e32 v152, v132, v140, vcc
	v_mov_b32_dpp v153, v94 row_ror:1 row_mask:0xf bank_mask:0xf
	v_mov_b32_dpp v154, v94 row_ror:2 row_mask:0xf bank_mask:0xf
	v_mov_b32_dpp v155, v95 row_ror:1 row_mask:0xf bank_mask:0xf
	v_mov_b32_dpp v156, v95 row_ror:2 row_mask:0xf bank_mask:0xf
	v_cndmask_b32_e32 v149, v131, v139, vcc
	v_cndmask_b32_e64 v140, v142, v154, s[42:43]
	v_cndmask_b32_e64 v141, v143, v156, s[42:43]
	v_cndmask_b32_e32 v150, v130, v138, vcc
	v_mov_b32_dpp v157, v96 row_ror:1 row_mask:0xf bank_mask:0xf
	v_mov_b32_dpp v158, v96 row_ror:2 row_mask:0xf bank_mask:0xf
	v_mov_b32_dpp v159, v97 row_ror:1 row_mask:0xf bank_mask:0xf
	v_mov_b32_dpp v160, v97 row_ror:2 row_mask:0xf bank_mask:0xf
	v_cndmask_b32_e32 v134, v153, v134, vcc
	v_cndmask_b32_e32 v135, v155, v135, vcc
	v_cndmask_b32_e64 v138, v144, v158, s[42:43]
	v_cndmask_b32_e64 v139, v145, v160, s[42:43]
	v_pk_fma_f32 v[140:141], v[118:119], v[140:141], v[102:103]
	v_cndmask_b32_e32 v136, v157, v136, vcc
	v_cndmask_b32_e32 v137, v159, v137, vcc
	v_pk_fma_f32 v[138:139], v[120:121], v[138:139], v[104:105]
	v_pk_fma_f32 v[134:135], v[114:115], v[134:135], v[140:141]
	v_pk_fma_f32 v[136:137], v[116:117], v[136:137], v[138:139]
	v_pk_fma_f32 v[94:95], v[94:95], v[106:107], v[134:135]
	v_mov_b32_dpp v138, v90 row_ror:1 row_mask:0xf bank_mask:0xf
	v_mov_b32_dpp v139, v90 row_ror:2 row_mask:0xf bank_mask:0xf
	v_mov_b32_dpp v140, v91 row_ror:1 row_mask:0xf bank_mask:0xf
	v_mov_b32_dpp v141, v91 row_ror:2 row_mask:0xf bank_mask:0xf
	v_mov_b32_dpp v142, v92 row_ror:1 row_mask:0xf bank_mask:0xf
	v_mov_b32_dpp v143, v92 row_ror:2 row_mask:0xf bank_mask:0xf
	v_mov_b32_dpp v144, v93 row_ror:1 row_mask:0xf bank_mask:0xf
	v_mov_b32_dpp v145, v93 row_ror:2 row_mask:0xf bank_mask:0xf
	s_nop 0
	v_cndmask_b32_e64 v134, v152, v143, s[42:43]
	v_cndmask_b32_e64 v135, v151, v145, s[42:43]
	v_cndmask_b32_e32 v132, v142, v132, vcc
	v_cndmask_b32_e32 v133, v144, v133, vcc
	v_pk_fma_f32 v[134:135], v[128:129], v[134:135], v[100:101]
	v_pk_fma_f32 v[96:97], v[96:97], v[108:109], v[136:137]
	v_pk_fma_f32 v[132:133], v[124:125], v[132:133], v[134:135]
	v_mul_f32_e32 v134, 0xbfb8aa3b, v94
	v_exp_f32_e32 v134, v134
	v_cndmask_b32_e64 v136, v150, v139, s[42:43]
	v_cndmask_b32_e64 v137, v149, v141, s[42:43]
	v_cndmask_b32_e32 v130, v138, v130, vcc
	v_cndmask_b32_e32 v131, v140, v131, vcc
	v_pk_fma_f32 v[136:137], v[126:127], v[136:137], v[98:99]
	v_pk_fma_f32 v[130:131], v[122:123], v[130:131], v[136:137]
	v_pk_fma_f32 v[92:93], v[92:93], v[112:113], v[132:133]
	v_pk_fma_f32 v[90:91], v[90:91], v[110:111], v[130:131]
	v_add_f32_e32 v130, 1.0, v134
	v_rcp_f32_e32 v130, v130
	v_mul_f32_e32 v131, 0xbfb8aa3b, v95
	v_exp_f32_e32 v131, v131
	v_mul_f32_e32 v94, v94, v130
	v_mul_f32_e32 v90, v94, v90
	v_add_f32_e32 v94, 1.0, v131
	v_mul_f32_e32 v130, 0xbfb8aa3b, v96
	v_rcp_f32_e32 v94, v94
	v_exp_f32_e32 v130, v130
	v_mul_f32_e32 v131, 0xbfb8aa3b, v97
	v_exp_f32_e32 v131, v131
	v_mul_f32_e32 v94, v95, v94
	v_add_f32_e32 v95, 1.0, v130
	v_rcp_f32_e32 v95, v95
	v_add_f32_e32 v130, 1.0, v131
	v_rcp_f32_e32 v130, v130
	v_mul_f32_e32 v91, v94, v91
	v_mul_f32_e32 v94, v96, v95
	v_mul_f32_e32 v92, v94, v92
	v_mul_f32_e32 v94, v97, v130
	v_mul_f32_e32 v93, v94, v93
	v_cvt_pk_bf16_f32 v90, v90, v91
	v_cvt_pk_bf16_f32 v91, v92, v93
	global_store_dwordx2 v[164:165], v[90:91], off offset:8
	v_mov_b32_dpp v130, v86 row_ror:1 row_mask:0xf bank_mask:0xf
	v_mov_b32_dpp v131, v86 row_ror:2 row_mask:0xf bank_mask:0xf
	v_mov_b32_dpp v132, v87 row_ror:1 row_mask:0xf bank_mask:0xf
	v_mov_b32_dpp v133, v87 row_ror:2 row_mask:0xf bank_mask:0xf
	v_mov_b32_dpp v134, v88 row_ror:1 row_mask:0xf bank_mask:0xf
	v_mov_b32_dpp v135, v88 row_ror:2 row_mask:0xf bank_mask:0xf
	v_mov_b32_dpp v136, v89 row_ror:1 row_mask:0xf bank_mask:0xf
	s_nop 0
	v_cndmask_b32_e64 v96, v154, v131, s[42:43]
	v_cndmask_b32_e64 v97, v156, v133, s[42:43]
	v_mov_b32_dpp v137, v89 row_ror:2 row_mask:0xf bank_mask:0xf
	v_cndmask_b32_e32 v90, v130, v153, vcc
	v_cndmask_b32_e32 v91, v132, v155, vcc
	v_cndmask_b32_e64 v94, v158, v135, s[42:43]
	v_cndmask_b32_e64 v95, v160, v137, s[42:43]
	v_pk_fma_f32 v[96:97], v[118:119], v[96:97], v[102:103]
	v_cndmask_b32_e32 v92, v134, v157, vcc
	v_cndmask_b32_e32 v93, v136, v159, vcc
	v_pk_fma_f32 v[94:95], v[120:121], v[94:95], v[104:105]
	v_pk_fma_f32 v[90:91], v[114:115], v[90:91], v[96:97]
	v_pk_fma_f32 v[92:93], v[116:117], v[92:93], v[94:95]
	v_pk_fma_f32 v[86:87], v[86:87], v[106:107], v[90:91]
	v_mov_b32_dpp v149, v82 row_ror:1 row_mask:0xf bank_mask:0xf
	v_mov_b32_dpp v150, v82 row_ror:2 row_mask:0xf bank_mask:0xf
	v_mov_b32_dpp v151, v83 row_ror:1 row_mask:0xf bank_mask:0xf
	v_mov_b32_dpp v152, v83 row_ror:2 row_mask:0xf bank_mask:0xf
	v_mov_b32_dpp v153, v84 row_ror:1 row_mask:0xf bank_mask:0xf
	v_mov_b32_dpp v154, v84 row_ror:2 row_mask:0xf bank_mask:0xf
	v_mov_b32_dpp v155, v85 row_ror:1 row_mask:0xf bank_mask:0xf
	v_mov_b32_dpp v156, v85 row_ror:2 row_mask:0xf bank_mask:0xf
	v_pk_fma_f32 v[88:89], v[88:89], v[108:109], v[92:93]
	v_cndmask_b32_e64 v94, v143, v154, s[42:43]
	v_cndmask_b32_e64 v95, v145, v156, s[42:43]
	v_cndmask_b32_e32 v92, v153, v142, vcc
	v_cndmask_b32_e32 v93, v155, v144, vcc
	v_pk_fma_f32 v[94:95], v[128:129], v[94:95], v[100:101]
	v_cndmask_b32_e64 v96, v139, v150, s[42:43]
	v_pk_fma_f32 v[92:93], v[124:125], v[92:93], v[94:95]
; __device__ __forceinline__ unsigned cvt_pk_bf16(float lo, float hi) { unsigned r; asm volatile("v_cvt_pk_bf16_f32 %0, %1, %2" : "=v"(r) : "v"(lo), "v"(hi)); return r; }
; DI float dpp_ror1(float x) { float r; asm volatile("s_nop 1\n\tv_mov_b32_dpp %0, %1 row_ror:1 row_mask:0xf bank_mask:0xf" : "=v"(r) : "v"(x)); return r; }
; DI float dpp_ror2(float x) { float r; asm volatile("s_nop 1\n\tv_mov_b32_dpp %0, %1 row_ror:2 row_mask:0xf bank_mask:0xf" : "=v"(r) : "v"(x)); return r; }
;     __device__ __forceinline__ void operator()(const f32x4 (&acc)[2][2][4][2], const Unit& u, int wr, int wc, int fr_in, int fq_in) const {
;     ...
; #pragma unroll
;                 for (int m = 0; m < 4; ++m) {
;                     f32x4 uu[2];
; #pragma unroll
;                     for (int bj = 0; bj < 2; ++bj) {
;                         const f32x4 cur = acc[ai][bj][m][n];
;                         f32x4 r1, r2;
; #pragma unroll
;                         for (int j = 0; j < 4; ++j) { r1[j] = dpp_ror1(cur[j]); r2[j] = dpp_ror2(cur[j]); }
;                         const f32x4 p1 = (fr >= 1) ? r1 : r1p[bj], p2 = (fr >= 2) ? r2 : r2p[bj];
;                         uu[bj] = w0[bj] * p2 + w1[bj] * p1 + w2[bj] * cur + bb[bj];
;                         r1p[bj] = r1; r2p[bj] = r2;
;                     }
;                     const int row = row0 + ai * HALF + m * 16;
;                     float a[4];
; #pragma unroll
;                     for (int j = 0; j < 4; ++j) { const float g = uu[0][j]; a[j] = g * __builtin_amdgcn_rcpf(1.f + __expf(-g)) * uu[1][j]; }
;                     u32x2 w; w.x = cvt_pk_bf16(a[0], a[1]); w.y = cvt_pk_bf16(a[2], a[3]);
;                     *(u32x2*)(ACT + (size_t)row * FFN + u.pn * HALF + wc * 32 + 8 * fq + 4 * n) = w;
	v_mul_f32_e32 v94, 0xbfb8aa3b, v86
	v_exp_f32_e32 v94, v94
	v_cndmask_b32_e64 v97, v141, v152, s[42:43]
	v_cndmask_b32_e32 v90, v149, v138, vcc
	v_cndmask_b32_e32 v91, v151, v140, vcc
	v_pk_fma_f32 v[96:97], v[126:127], v[96:97], v[98:99]
	v_pk_fma_f32 v[90:91], v[122:123], v[90:91], v[96:97]
	v_pk_fma_f32 v[84:85], v[84:85], v[112:113], v[92:93]
	v_pk_fma_f32 v[82:83], v[82:83], v[110:111], v[90:91]
	v_add_f32_e32 v90, 1.0, v94
	v_rcp_f32_e32 v90, v90
	v_mul_f32_e32 v91, 0xbfb8aa3b, v87
	v_exp_f32_e32 v91, v91
	v_mul_f32_e32 v86, v86, v90
	v_mul_f32_e32 v82, v86, v82
	v_add_f32_e32 v86, 1.0, v91
	v_mul_f32_e32 v90, 0xbfb8aa3b, v88
	v_rcp_f32_e32 v86, v86
	v_exp_f32_e32 v90, v90
	v_mul_f32_e32 v91, 0xbfb8aa3b, v89
	v_exp_f32_e32 v91, v91
	v_mul_f32_e32 v86, v87, v86
	v_add_f32_e32 v87, 1.0, v90
	v_rcp_f32_e32 v87, v87
	v_add_f32_e32 v90, 1.0, v91
	v_rcp_f32_e32 v90, v90
	v_mul_f32_e32 v83, v86, v83
	v_mul_f32_e32 v86, v88, v87
	v_mul_f32_e32 v84, v86, v84
	v_mul_f32_e32 v86, v89, v90
	v_mul_f32_e32 v85, v86, v85
	v_cvt_pk_bf16_f32 v82, v82, v83
	v_cvt_pk_bf16_f32 v83, v84, v85
	global_store_dwordx2 v[166:167], v[82:83], off offset:8
	v_mov_b32_dpp v90, v78 row_ror:1 row_mask:0xf bank_mask:0xf
	v_mov_b32_dpp v91, v78 row_ror:2 row_mask:0xf bank_mask:0xf
	v_mov_b32_dpp v92, v79 row_ror:1 row_mask:0xf bank_mask:0xf
	v_mov_b32_dpp v93, v79 row_ror:2 row_mask:0xf bank_mask:0xf
	v_mov_b32_dpp v94, v80 row_ror:1 row_mask:0xf bank_mask:0xf
	v_mov_b32_dpp v95, v80 row_ror:2 row_mask:0xf bank_mask:0xf
	v_mov_b32_dpp v96, v81 row_ror:1 row_mask:0xf bank_mask:0xf
	s_nop 0
	v_cndmask_b32_e64 v88, v131, v91, s[42:43]
	v_cndmask_b32_e64 v89, v133, v93, s[42:43]
	v_mov_b32_dpp v97, v81 row_ror:2 row_mask:0xf bank_mask:0xf
	v_cndmask_b32_e32 v82, v90, v130, vcc
	v_cndmask_b32_e32 v83, v92, v132, vcc
	v_cndmask_b32_e64 v86, v135, v95, s[42:43]
	v_cndmask_b32_e64 v87, v137, v97, s[42:43]
	v_pk_fma_f32 v[88:89], v[118:119], v[88:89], v[102:103]
	v_cndmask_b32_e32 v84, v94, v134, vcc
	v_cndmask_b32_e32 v85, v96, v136, vcc
	v_pk_fma_f32 v[86:87], v[120:121], v[86:87], v[104:105]
	v_pk_fma_f32 v[82:83], v[114:115], v[82:83], v[88:89]
	v_pk_fma_f32 v[84:85], v[116:117], v[84:85], v[86:87]
	v_pk_fma_f32 v[78:79], v[78:79], v[106:107], v[82:83]
	v_mov_b32_dpp v130, v74 row_ror:1 row_mask:0xf bank_mask:0xf
	v_mov_b32_dpp v131, v74 row_ror:2 row_mask:0xf bank_mask:0xf
	v_mov_b32_dpp v132, v75 row_ror:1 row_mask:0xf bank_mask:0xf
	v_mov_b32_dpp v133, v75 row_ror:2 row_mask:0xf bank_mask:0xf
	v_mov_b32_dpp v134, v76 row_ror:1 row_mask:0xf bank_mask:0xf
	v_mov_b32_dpp v135, v76 row_ror:2 row_mask:0xf bank_mask:0xf
	v_mov_b32_dpp v136, v77 row_ror:1 row_mask:0xf bank_mask:0xf
	v_mov_b32_dpp v137, v77 row_ror:2 row_mask:0xf bank_mask:0xf
	v_pk_fma_f32 v[80:81], v[80:81], v[108:109], v[84:85]
	v_cndmask_b32_e64 v86, v154, v135, s[42:43]
	v_cndmask_b32_e64 v87, v156, v137, s[42:43]
	v_cndmask_b32_e32 v84, v134, v153, vcc
	v_cndmask_b32_e32 v85, v136, v155, vcc
	v_pk_fma_f32 v[86:87], v[128:129], v[86:87], v[100:101]
	v_cndmask_b32_e64 v88, v150, v131, s[42:43]
	v_pk_fma_f32 v[84:85], v[124:125], v[84:85], v[86:87]
	v_mul_f32_e32 v86, 0xbfb8aa3b, v78
	v_exp_f32_e32 v86, v86
	v_cndmask_b32_e64 v89, v152, v133, s[42:43]
	v_cndmask_b32_e32 v82, v130, v149, vcc
	v_cndmask_b32_e32 v83, v132, v151, vcc
	v_pk_fma_f32 v[88:89], v[126:127], v[88:89], v[98:99]
	v_pk_fma_f32 v[82:83], v[122:123], v[82:83], v[88:89]
	v_pk_fma_f32 v[76:77], v[76:77], v[112:113], v[84:85]
	v_pk_fma_f32 v[74:75], v[74:75], v[110:111], v[82:83]
	v_add_f32_e32 v82, 1.0, v86
	v_rcp_f32_e32 v82, v82
	v_mul_f32_e32 v83, 0xbfb8aa3b, v79
	v_exp_f32_e32 v83, v83
	v_mul_f32_e32 v78, v78, v82
	v_mul_f32_e32 v74, v78, v74
	v_add_f32_e32 v78, 1.0, v83
	v_mul_f32_e32 v82, 0xbfb8aa3b, v80
	v_rcp_f32_e32 v78, v78
	v_exp_f32_e32 v82, v82
	v_mul_f32_e32 v83, 0xbfb8aa3b, v81
	v_exp_f32_e32 v83, v83
	v_mul_f32_e32 v78, v79, v78
	v_add_f32_e32 v79, 1.0, v82
	v_rcp_f32_e32 v79, v79
; __device__ __forceinline__ unsigned cvt_pk_bf16(float lo, float hi) { unsigned r; asm volatile("v_cvt_pk_bf16_f32 %0, %1, %2" : "=v"(r) : "v"(lo), "v"(hi)); return r; }
;     __device__ __forceinline__ void operator()(const f32x4 (&acc)[2][2][4][2], const Unit& u, int wr, int wc, int fr_in, int fq_in) const {
;     ...
;                 for (int bj = 0; bj < 2; ++bj) {
;                     const int tcol = bj * HALF + wc * 32 + 8 * fq + 4 * n;
;                     w0[bj] = *(const f32x4*)(cwl + eo + tcol); w1[bj] = *(const f32x4*)(cwl + eo + 256 + tcol); w2[bj] = *(const f32x4*)(cwl + eo + 512 + tcol); bb[bj] = *(const f32x4*)(cwl + eo + 768 + tcol);
;                     f32x4 E0 = (f32x4){0.f, 0.f, 0.f, 0.f}, E1 = E0;
;                     if (fr < 2) {
;                         if (wr == 1 || ai == 1) {
;                             const int sai = (wr == 1) ? ai : 0, swr = (wr == 1) ? 0 : 1;
;                             const int e = (((((sai * 2 + swr) * 4 + wc) * 2 + bj) * 2 + n) * 4 + fq) * 2;
;                             E0 = ex[e]; E1 = ex[e + 1];
;                         }
;                     }
;                     r1p[bj] = E1; r2p[bj] = (fr == 0) ? E0 : E1;
;     ...
; #pragma unroll
;                 for (int m = 0; m < 4; ++m) {
;                     f32x4 uu[2];
; #pragma unroll
;                     for (int bj = 0; bj < 2; ++bj) {
;                         const f32x4 cur = acc[ai][bj][m][n];
;                         f32x4 r1, r2;
; #pragma unroll
;                         for (int j = 0; j < 4; ++j) { r1[j] = dpp_ror1(cur[j]); r2[j] = dpp_ror2(cur[j]); }
;                         const f32x4 p1 = (fr >= 1) ? r1 : r1p[bj], p2 = (fr >= 2) ? r2 : r2p[bj];
;                         uu[bj] = w0[bj] * p2 + w1[bj] * p1 + w2[bj] * cur + bb[bj];
;                         r1p[bj] = r1; r2p[bj] = r2;
;                     }
;                     const int row = row0 + ai * HALF + m * 16;
;                     float a[4];
; #pragma unroll
;                     for (int j = 0; j < 4; ++j) { const float g = uu[0][j]; a[j] = g * __builtin_amdgcn_rcpf(1.f + __expf(-g)) * uu[1][j]; }
;                     u32x2 w; w.x = cvt_pk_bf16(a[0], a[1]); w.y = cvt_pk_bf16(a[2], a[3]);
;                     *(u32x2*)(ACT + (size_t)row * FFN + u.pn * HALF + wc * 32 + 8 * fq + 4 * n) = w;
	v_add_f32_e32 v82, 1.0, v83
	v_rcp_f32_e32 v82, v82
	v_mul_f32_e32 v75, v78, v75
	v_mul_f32_e32 v78, v80, v79
	v_mul_f32_e32 v76, v78, v76
	v_mul_f32_e32 v78, v81, v82
	v_mul_f32_e32 v77, v78, v77
	v_cvt_pk_bf16_f32 v74, v74, v75
	v_cvt_pk_bf16_f32 v75, v76, v77
	global_store_dwordx2 v[168:169], v[74:75], off offset:8
	v_mov_b32_dpp v74, v70 row_ror:1 row_mask:0xf bank_mask:0xf
	v_mov_b32_dpp v80, v70 row_ror:2 row_mask:0xf bank_mask:0xf
	v_mov_b32_dpp v75, v71 row_ror:1 row_mask:0xf bank_mask:0xf
	v_mov_b32_dpp v81, v71 row_ror:2 row_mask:0xf bank_mask:0xf
	v_mov_b32_dpp v76, v72 row_ror:1 row_mask:0xf bank_mask:0xf
	v_mov_b32_dpp v78, v72 row_ror:2 row_mask:0xf bank_mask:0xf
	v_mov_b32_dpp v77, v73 row_ror:1 row_mask:0xf bank_mask:0xf
	v_mov_b32_dpp v79, v73 row_ror:2 row_mask:0xf bank_mask:0xf
	s_nop 0
	v_cndmask_b32_e64 v80, v91, v80, s[42:43]
	v_cndmask_b32_e64 v78, v95, v78, s[42:43]
	v_cndmask_b32_e64 v79, v97, v79, s[42:43]
	v_cndmask_b32_e64 v81, v93, v81, s[42:43]
	v_cndmask_b32_e32 v74, v74, v90, vcc
	v_cndmask_b32_e32 v75, v75, v92, vcc
	v_cndmask_b32_e32 v76, v76, v94, vcc
	v_cndmask_b32_e32 v77, v77, v96, vcc
	v_pk_fma_f32 v[80:81], v[118:119], v[80:81], v[102:103]
	v_pk_fma_f32 v[78:79], v[120:121], v[78:79], v[104:105]
	v_pk_fma_f32 v[74:75], v[114:115], v[74:75], v[80:81]
	v_pk_fma_f32 v[76:77], v[116:117], v[76:77], v[78:79]
	v_pk_fma_f32 v[70:71], v[70:71], v[106:107], v[74:75]
	v_pk_fma_f32 v[72:73], v[72:73], v[108:109], v[76:77]
	v_mov_b32_dpp v74, v66 row_ror:1 row_mask:0xf bank_mask:0xf
	v_mov_b32_dpp v80, v66 row_ror:2 row_mask:0xf bank_mask:0xf
	v_mov_b32_dpp v75, v67 row_ror:1 row_mask:0xf bank_mask:0xf
	v_mov_b32_dpp v81, v67 row_ror:2 row_mask:0xf bank_mask:0xf
	v_mov_b32_dpp v76, v68 row_ror:1 row_mask:0xf bank_mask:0xf
	v_mov_b32_dpp v78, v68 row_ror:2 row_mask:0xf bank_mask:0xf
	v_mov_b32_dpp v77, v69 row_ror:1 row_mask:0xf bank_mask:0xf
	v_mov_b32_dpp v79, v69 row_ror:2 row_mask:0xf bank_mask:0xf
	v_cndmask_b32_e64 v78, v135, v78, s[42:43]
	v_cndmask_b32_e64 v79, v137, v79, s[42:43]
	v_cndmask_b32_e32 v76, v76, v134, vcc
	v_cndmask_b32_e32 v77, v77, v136, vcc
	v_pk_fma_f32 v[78:79], v[128:129], v[78:79], v[100:101]
	v_cndmask_b32_e64 v80, v131, v80, s[42:43]
	v_pk_fma_f32 v[76:77], v[124:125], v[76:77], v[78:79]
	v_mul_f32_e32 v78, 0xbfb8aa3b, v70
	v_exp_f32_e32 v78, v78
	v_cndmask_b32_e64 v81, v133, v81, s[42:43]
	v_cndmask_b32_e32 v74, v74, v130, vcc
	v_cndmask_b32_e32 v75, v75, v132, vcc
	v_pk_fma_f32 v[80:81], v[126:127], v[80:81], v[98:99]
	v_pk_fma_f32 v[74:75], v[122:123], v[74:75], v[80:81]
	v_pk_fma_f32 v[68:69], v[68:69], v[112:113], v[76:77]
	v_pk_fma_f32 v[66:67], v[66:67], v[110:111], v[74:75]
	v_add_f32_e32 v74, 1.0, v78
	v_rcp_f32_e32 v74, v74
	v_mul_f32_e32 v75, 0xbfb8aa3b, v71
	v_exp_f32_e32 v75, v75
	v_mul_f32_e32 v70, v70, v74
	v_mul_f32_e32 v66, v70, v66
	v_add_f32_e32 v70, 1.0, v75
	v_mul_f32_e32 v74, 0xbfb8aa3b, v72
	v_rcp_f32_e32 v70, v70
	v_exp_f32_e32 v74, v74
	v_mul_f32_e32 v75, 0xbfb8aa3b, v73
	v_exp_f32_e32 v75, v75
	v_mul_f32_e32 v70, v71, v70
	v_add_f32_e32 v71, 1.0, v74
	v_rcp_f32_e32 v71, v71
	v_add_f32_e32 v74, 1.0, v75
	v_rcp_f32_e32 v74, v74
	v_mul_f32_e32 v67, v70, v67
	v_mul_f32_e32 v70, v72, v71
	v_mul_f32_e32 v68, v70, v68
	v_mul_f32_e32 v70, v73, v74
	v_mul_f32_e32 v69, v70, v69
	v_cvt_pk_bf16_f32 v66, v66, v67
	v_cvt_pk_bf16_f32 v67, v68, v69
	global_store_dwordx2 v[146:147], v[66:67], off offset:8
	ds_read_b128 v[86:89], v214
	ds_read_b128 v[82:85], v214 offset:1024
	ds_read_b128 v[74:77], v214 offset:2048
	ds_read_b128 v[70:73], v214 offset:3072
	v_mov_b32_e32 v106, 0
	v_mov_b32_e32 v110, 0
	v_mov_b32_e32 v111, 0
	v_mov_b32_e32 v112, 0
	v_mov_b32_e32 v113, 0
	v_mov_b32_e32 v102, 0
	v_mov_b32_e32 v103, 0
	v_mov_b32_e32 v104, 0
	v_mov_b32_e32 v105, 0
	s_and_saveexec_b64 s[48:49], s[44:45]
	s_cbranch_execz .LBB0_726
	s_lshl_b32 s2, s97, 4
	v_add3_u32 v66, v213, v215, s2
	ds_read_b128 v[110:113], v66
	ds_read_b128 v[102:105], v66 offset:16

; __device__ __forceinline__ unsigned cvt_pk_bf16(float lo, float hi) { unsigned r; asm volatile("v_cvt_pk_bf16_f32 %0, %1, %2" : "=v"(r) : "v"(lo), "v"(hi)); return r; }
; DI float dpp_ror1(float x) { float r; asm volatile("s_nop 1\n\tv_mov_b32_dpp %0, %1 row_ror:1 row_mask:0xf bank_mask:0xf" : "=v"(r) : "v"(x)); return r; }
; DI float dpp_ror2(float x) { float r; asm volatile("s_nop 1\n\tv_mov_b32_dpp %0, %1 row_ror:2 row_mask:0xf bank_mask:0xf" : "=v"(r) : "v"(x)); return r; }
;     __device__ __forceinline__ void operator()(const f32x4 (&acc)[2][2][4][2], const Unit& u, int wr, int wc, int fr_in, int fq_in) const {
;     ...
; #pragma unroll
;                 for (int m = 0; m < 4; ++m) {
;                     f32x4 uu[2];
; #pragma unroll
;                     for (int bj = 0; bj < 2; ++bj) {
;                         const f32x4 cur = acc[ai][bj][m][n];
;                         f32x4 r1, r2;
; #pragma unroll
;                         for (int j = 0; j < 4; ++j) { r1[j] = dpp_ror1(cur[j]); r2[j] = dpp_ror2(cur[j]); }
;                         const f32x4 p1 = (fr >= 1) ? r1 : r1p[bj], p2 = (fr >= 2) ? r2 : r2p[bj];
;                         uu[bj] = w0[bj] * p2 + w1[bj] * p1 + w2[bj] * cur + bb[bj];
;                         r1p[bj] = r1; r2p[bj] = r2;
;                     }
;                     const int row = row0 + ai * HALF + m * 16;
;                     float a[4];
; #pragma unroll
;                     for (int j = 0; j < 4; ++j) { const float g = uu[0][j]; a[j] = g * __builtin_amdgcn_rcpf(1.f + __expf(-g)) * uu[1][j]; }
;                     u32x2 w; w.x = cvt_pk_bf16(a[0], a[1]); w.y = cvt_pk_bf16(a[2], a[3]);
;                     *(u32x2*)(ACT + (size_t)row * FFN + u.pn * HALF + wc * 32 + 8 * fq + 4 * n) = w;
.LBB0_728:
	s_or_b64 exec, exec, s[48:49]
	s_waitcnt lgkmcnt(0)
	v_cndmask_b32_e32 v111, v103, v111, vcc
	v_cndmask_b32_e32 v110, v102, v110, vcc
	v_cndmask_b32_e32 v113, v105, v113, vcc
	v_cndmask_b32_e32 v112, v104, v112, vcc
	v_cndmask_b32_e32 v117, v101, v109, vcc
	v_cndmask_b32_e32 v118, v100, v108, vcc
	v_mov_b32_dpp v119, v62 row_ror:1 row_mask:0xf bank_mask:0xf
	v_mov_b32_dpp v120, v62 row_ror:2 row_mask:0xf bank_mask:0xf
	v_mov_b32_dpp v121, v63 row_ror:1 row_mask:0xf bank_mask:0xf
	v_mov_b32_dpp v122, v63 row_ror:2 row_mask:0xf bank_mask:0xf
	v_cndmask_b32_e32 v115, v99, v107, vcc
	v_cndmask_b32_e64 v108, v110, v120, s[42:43]
	v_cndmask_b32_e64 v109, v111, v122, s[42:43]
	v_cndmask_b32_e32 v116, v98, v106, vcc
	v_mov_b32_dpp v123, v64 row_ror:1 row_mask:0xf bank_mask:0xf
	v_mov_b32_dpp v124, v64 row_ror:2 row_mask:0xf bank_mask:0xf
	v_mov_b32_dpp v125, v65 row_ror:1 row_mask:0xf bank_mask:0xf
	v_mov_b32_dpp v126, v65 row_ror:2 row_mask:0xf bank_mask:0xf
	v_cndmask_b32_e32 v102, v119, v102, vcc
	v_cndmask_b32_e32 v103, v121, v103, vcc
	v_cndmask_b32_e64 v106, v112, v124, s[42:43]
	v_cndmask_b32_e64 v107, v113, v126, s[42:43]
	v_pk_fma_f32 v[108:109], v[86:87], v[108:109], v[70:71]
	v_cndmask_b32_e32 v104, v123, v104, vcc
	v_cndmask_b32_e32 v105, v125, v105, vcc
	v_pk_fma_f32 v[106:107], v[88:89], v[106:107], v[72:73]
	v_pk_fma_f32 v[102:103], v[82:83], v[102:103], v[108:109]
	v_pk_fma_f32 v[104:105], v[84:85], v[104:105], v[106:107]
	v_pk_fma_f32 v[62:63], v[62:63], v[74:75], v[102:103]
	v_mov_b32_dpp v106, v58 row_ror:1 row_mask:0xf bank_mask:0xf
	v_mov_b32_dpp v107, v58 row_ror:2 row_mask:0xf bank_mask:0xf
	v_mov_b32_dpp v108, v59 row_ror:1 row_mask:0xf bank_mask:0xf
	v_mov_b32_dpp v109, v59 row_ror:2 row_mask:0xf bank_mask:0xf
	v_mov_b32_dpp v110, v60 row_ror:1 row_mask:0xf bank_mask:0xf
	v_mov_b32_dpp v111, v60 row_ror:2 row_mask:0xf bank_mask:0xf
	v_mov_b32_dpp v112, v61 row_ror:1 row_mask:0xf bank_mask:0xf
	v_mov_b32_dpp v113, v61 row_ror:2 row_mask:0xf bank_mask:0xf
	s_nop 0
	v_cndmask_b32_e64 v102, v118, v111, s[42:43]
	v_cndmask_b32_e64 v103, v117, v113, s[42:43]
	v_cndmask_b32_e32 v100, v110, v100, vcc
	v_cndmask_b32_e32 v101, v112, v101, vcc
	v_pk_fma_f32 v[102:103], v[96:97], v[102:103], v[68:69]
	v_pk_fma_f32 v[64:65], v[64:65], v[76:77], v[104:105]
	v_pk_fma_f32 v[100:101], v[92:93], v[100:101], v[102:103]
	v_mul_f32_e32 v102, 0xbfb8aa3b, v62
	v_exp_f32_e32 v102, v102
	v_cndmask_b32_e64 v104, v116, v107, s[42:43]
	v_cndmask_b32_e64 v105, v115, v109, s[42:43]
	v_cndmask_b32_e32 v98, v106, v98, vcc
	v_cndmask_b32_e32 v99, v108, v99, vcc
	v_pk_fma_f32 v[104:105], v[94:95], v[104:105], v[66:67]
	v_pk_fma_f32 v[98:99], v[90:91], v[98:99], v[104:105]
	v_pk_fma_f32 v[60:61], v[60:61], v[80:81], v[100:101]
	v_pk_fma_f32 v[58:59], v[58:59], v[78:79], v[98:99]
	v_add_f32_e32 v98, 1.0, v102
	v_rcp_f32_e32 v98, v98
	v_mul_f32_e32 v99, 0xbfb8aa3b, v63
	v_exp_f32_e32 v99, v99
	v_mul_f32_e32 v62, v62, v98
	v_mul_f32_e32 v58, v62, v58
	v_add_f32_e32 v62, 1.0, v99
	v_mul_f32_e32 v98, 0xbfb8aa3b, v64
	v_rcp_f32_e32 v62, v62
	v_exp_f32_e32 v98, v98
	v_mul_f32_e32 v99, 0xbfb8aa3b, v65
	v_exp_f32_e32 v99, v99
	v_mul_f32_e32 v62, v63, v62
	v_add_f32_e32 v63, 1.0, v98
	v_rcp_f32_e32 v63, v63
	v_add_f32_e32 v98, 1.0, v99
	v_rcp_f32_e32 v98, v98
	v_mul_f32_e32 v59, v62, v59
	v_mul_f32_e32 v62, v64, v63
	v_readlane_b32 s8, v240, 27
	v_mul_f32_e32 v62, v62, v60
	v_mul_f32_e32 v60, v65, v98
	v_readlane_b32 s9, v240, 28
	v_add_u32_e32 v114, 0x80, v174
	v_mul_f32_e32 v61, v60, v61
	v_cvt_pk_bf16_f32 v60, v58, v59
	v_mov_b64_e32 v[58:59], s[8:9]
	v_cvt_pk_bf16_f32 v61, v62, v61
	v_mad_i64_i32 v[62:63], s[22:23], v114, s25, v[58:59]
	v_lshl_add_u64 v[62:63], v[62:63], 0, s[46:47]
	v_lshl_add_u64 v[62:63], v[62:63], 0, s[62:63]
	v_lshl_add_u64 v[98:99], v[62:63], 0, v[162:163]
	global_store_dwordx2 v[98:99], v[60:61], off
	v_mov_b32_dpp v102, v54 row_ror:1 row_mask:0xf bank_mask:0xf
	v_mov_b32_dpp v103, v54 row_ror:2 row_mask:0xf bank_mask:0xf
	v_mov_b32_dpp v104, v55 row_ror:1 row_mask:0xf bank_mask:0xf
	v_mov_b32_dpp v105, v55 row_ror:2 row_mask:0xf bank_mask:0xf
	v_mov_b32_dpp v114, v56 row_ror:1 row_mask:0xf bank_mask:0xf
	v_mov_b32_dpp v115, v56 row_ror:2 row_mask:0xf bank_mask:0xf
	v_mov_b32_dpp v116, v57 row_ror:1 row_mask:0xf bank_mask:0xf
	s_nop 0
	v_cndmask_b32_e64 v100, v120, v103, s[42:43]
	v_cndmask_b32_e64 v101, v122, v105, s[42:43]
	v_mov_b32_dpp v117, v57 row_ror:2 row_mask:0xf bank_mask:0xf
	v_cndmask_b32_e32 v60, v102, v119, vcc
	v_cndmask_b32_e32 v61, v104, v121, vcc
	v_cndmask_b32_e64 v64, v124, v115, s[42:43]
	v_cndmask_b32_e64 v65, v126, v117, s[42:43]
	v_pk_fma_f32 v[100:101], v[86:87], v[100:101], v[70:71]
	v_cndmask_b32_e32 v62, v114, v123, vcc
	v_cndmask_b32_e32 v63, v116, v125, vcc
	v_pk_fma_f32 v[64:65], v[88:89], v[64:65], v[72:73]
	v_pk_fma_f32 v[60:61], v[82:83], v[60:61], v[100:101]
	v_pk_fma_f32 v[62:63], v[84:85], v[62:63], v[64:65]
	v_pk_fma_f32 v[54:55], v[54:55], v[74:75], v[60:61]
	v_mov_b32_dpp v118, v50 row_ror:1 row_mask:0xf bank_mask:0xf
	v_mov_b32_dpp v119, v50 row_ror:2 row_mask:0xf bank_mask:0xf
	v_mov_b32_dpp v120, v51 row_ror:1 row_mask:0xf bank_mask:0xf
	v_mov_b32_dpp v121, v51 row_ror:2 row_mask:0xf bank_mask:0xf
	v_mov_b32_dpp v122, v52 row_ror:1 row_mask:0xf bank_mask:0xf
	v_mov_b32_dpp v123, v52 row_ror:2 row_mask:0xf bank_mask:0xf
	v_mov_b32_dpp v124, v53 row_ror:1 row_mask:0xf bank_mask:0xf
	v_mov_b32_dpp v125, v53 row_ror:2 row_mask:0xf bank_mask:0xf
	v_pk_fma_f32 v[56:57], v[56:57], v[76:77], v[62:63]
	v_cndmask_b32_e64 v64, v111, v123, s[42:43]
	v_cndmask_b32_e64 v65, v113, v125, s[42:43]
; __device__ __forceinline__ unsigned cvt_pk_bf16(float lo, float hi) { unsigned r; asm volatile("v_cvt_pk_bf16_f32 %0, %1, %2" : "=v"(r) : "v"(lo), "v"(hi)); return r; }
; DI float dpp_ror1(float x) { float r; asm volatile("s_nop 1\n\tv_mov_b32_dpp %0, %1 row_ror:1 row_mask:0xf bank_mask:0xf" : "=v"(r) : "v"(x)); return r; }
; DI float dpp_ror2(float x) { float r; asm volatile("s_nop 1\n\tv_mov_b32_dpp %0, %1 row_ror:2 row_mask:0xf bank_mask:0xf" : "=v"(r) : "v"(x)); return r; }
;     __device__ __forceinline__ void operator()(const f32x4 (&acc)[2][2][4][2], const Unit& u, int wr, int wc, int fr_in, int fq_in) const {
;     ...
; #pragma unroll
;                 for (int m = 0; m < 4; ++m) {
;                     f32x4 uu[2];
; #pragma unroll
;                     for (int bj = 0; bj < 2; ++bj) {
;                         const f32x4 cur = acc[ai][bj][m][n];
;                         f32x4 r1, r2;
; #pragma unroll
;                         for (int j = 0; j < 4; ++j) { r1[j] = dpp_ror1(cur[j]); r2[j] = dpp_ror2(cur[j]); }
;                         const f32x4 p1 = (fr >= 1) ? r1 : r1p[bj], p2 = (fr >= 2) ? r2 : r2p[bj];
;                         uu[bj] = w0[bj] * p2 + w1[bj] * p1 + w2[bj] * cur + bb[bj];
;                         r1p[bj] = r1; r2p[bj] = r2;
;                     }
;                     const int row = row0 + ai * HALF + m * 16;
;                     float a[4];
; #pragma unroll
;                     for (int j = 0; j < 4; ++j) { const float g = uu[0][j]; a[j] = g * __builtin_amdgcn_rcpf(1.f + __expf(-g)) * uu[1][j]; }
;                     u32x2 w; w.x = cvt_pk_bf16(a[0], a[1]); w.y = cvt_pk_bf16(a[2], a[3]);
;                     *(u32x2*)(ACT + (size_t)row * FFN + u.pn * HALF + wc * 32 + 8 * fq + 4 * n) = w;
	v_cndmask_b32_e32 v62, v122, v110, vcc
	v_cndmask_b32_e32 v63, v124, v112, vcc
	v_pk_fma_f32 v[64:65], v[96:97], v[64:65], v[68:69]
	v_cndmask_b32_e64 v100, v107, v119, s[42:43]
	v_pk_fma_f32 v[62:63], v[92:93], v[62:63], v[64:65]
	v_mul_f32_e32 v64, 0xbfb8aa3b, v54
	v_exp_f32_e32 v64, v64
	v_cndmask_b32_e64 v101, v109, v121, s[42:43]
	v_cndmask_b32_e32 v60, v118, v106, vcc
	v_cndmask_b32_e32 v61, v120, v108, vcc
	v_pk_fma_f32 v[100:101], v[94:95], v[100:101], v[66:67]
	v_pk_fma_f32 v[60:61], v[90:91], v[60:61], v[100:101]
	v_pk_fma_f32 v[52:53], v[52:53], v[80:81], v[62:63]
	v_pk_fma_f32 v[50:51], v[50:51], v[78:79], v[60:61]
	v_add_f32_e32 v60, 1.0, v64
	v_rcp_f32_e32 v60, v60
	v_mul_f32_e32 v61, 0xbfb8aa3b, v55
	v_exp_f32_e32 v61, v61
	v_mul_f32_e32 v54, v54, v60
	v_mul_f32_e32 v50, v54, v50
	v_add_f32_e32 v54, 1.0, v61
	v_mul_f32_e32 v60, 0xbfb8aa3b, v56
	v_rcp_f32_e32 v54, v54
	v_exp_f32_e32 v60, v60
	v_mul_f32_e32 v61, 0xbfb8aa3b, v57
	v_exp_f32_e32 v61, v61
	v_mul_f32_e32 v54, v55, v54
	v_add_f32_e32 v55, 1.0, v60
	v_rcp_f32_e32 v55, v55
	v_add_f32_e32 v60, 1.0, v61
	v_rcp_f32_e32 v60, v60
	v_mul_f32_e32 v51, v54, v51
	v_mul_f32_e32 v54, v56, v55
	v_mul_f32_e32 v52, v54, v52
	v_mul_f32_e32 v54, v57, v60
	v_mul_f32_e32 v53, v54, v53
	v_add_u32_e32 v54, 0x90, v174
	v_cvt_pk_bf16_f32 v50, v50, v51
	v_cvt_pk_bf16_f32 v51, v52, v53
	v_mad_i64_i32 v[52:53], s[22:23], v54, s25, v[58:59]
	v_lshl_add_u64 v[52:53], v[52:53], 0, s[46:47]
	v_lshl_add_u64 v[52:53], v[52:53], 0, s[62:63]
	v_lshl_add_u64 v[100:101], v[52:53], 0, v[162:163]
	global_store_dwordx2 v[100:101], v[50:51], off
	v_mov_b32_dpp v60, v46 row_ror:1 row_mask:0xf bank_mask:0xf
	v_mov_b32_dpp v61, v46 row_ror:2 row_mask:0xf bank_mask:0xf
	v_mov_b32_dpp v62, v47 row_ror:1 row_mask:0xf bank_mask:0xf
	v_mov_b32_dpp v63, v47 row_ror:2 row_mask:0xf bank_mask:0xf
	v_mov_b32_dpp v64, v48 row_ror:1 row_mask:0xf bank_mask:0xf
	v_mov_b32_dpp v65, v48 row_ror:2 row_mask:0xf bank_mask:0xf
	v_mov_b32_dpp v106, v49 row_ror:1 row_mask:0xf bank_mask:0xf
	s_nop 0
	v_cndmask_b32_e64 v56, v103, v61, s[42:43]
	v_cndmask_b32_e64 v57, v105, v63, s[42:43]
	v_mov_b32_dpp v107, v49 row_ror:2 row_mask:0xf bank_mask:0xf
	v_cndmask_b32_e32 v50, v60, v102, vcc
	v_cndmask_b32_e32 v51, v62, v104, vcc
	v_cndmask_b32_e64 v54, v115, v65, s[42:43]
	v_cndmask_b32_e64 v55, v117, v107, s[42:43]
	v_pk_fma_f32 v[56:57], v[86:87], v[56:57], v[70:71]
	v_cndmask_b32_e32 v52, v64, v114, vcc
	v_cndmask_b32_e32 v53, v106, v116, vcc
	v_pk_fma_f32 v[54:55], v[88:89], v[54:55], v[72:73]
	v_pk_fma_f32 v[50:51], v[82:83], v[50:51], v[56:57]
	v_pk_fma_f32 v[52:53], v[84:85], v[52:53], v[54:55]
	v_pk_fma_f32 v[46:47], v[46:47], v[74:75], v[50:51]
	v_mov_b32_dpp v104, v42 row_ror:1 row_mask:0xf bank_mask:0xf
	v_mov_b32_dpp v105, v42 row_ror:2 row_mask:0xf bank_mask:0xf
	v_mov_b32_dpp v108, v43 row_ror:1 row_mask:0xf bank_mask:0xf
	v_mov_b32_dpp v109, v43 row_ror:2 row_mask:0xf bank_mask:0xf
	v_mov_b32_dpp v110, v44 row_ror:1 row_mask:0xf bank_mask:0xf
	v_mov_b32_dpp v111, v44 row_ror:2 row_mask:0xf bank_mask:0xf
	v_mov_b32_dpp v112, v45 row_ror:1 row_mask:0xf bank_mask:0xf
	v_mov_b32_dpp v113, v45 row_ror:2 row_mask:0xf bank_mask:0xf
	v_pk_fma_f32 v[48:49], v[48:49], v[76:77], v[52:53]
	v_cndmask_b32_e64 v54, v123, v111, s[42:43]
	v_cndmask_b32_e64 v55, v125, v113, s[42:43]
	v_cndmask_b32_e32 v52, v110, v122, vcc
	v_cndmask_b32_e32 v53, v112, v124, vcc
	v_pk_fma_f32 v[54:55], v[96:97], v[54:55], v[68:69]
	v_cndmask_b32_e64 v56, v119, v105, s[42:43]
	v_pk_fma_f32 v[52:53], v[92:93], v[52:53], v[54:55]
	v_mul_f32_e32 v54, 0xbfb8aa3b, v46
	v_exp_f32_e32 v54, v54
	v_cndmask_b32_e64 v57, v121, v109, s[42:43]
	v_cndmask_b32_e32 v50, v104, v118, vcc
	v_cndmask_b32_e32 v51, v108, v120, vcc
	v_pk_fma_f32 v[56:57], v[94:95], v[56:57], v[66:67]
	v_pk_fma_f32 v[50:51], v[90:91], v[50:51], v[56:57]
	v_pk_fma_f32 v[44:45], v[44:45], v[80:81], v[52:53]
	v_pk_fma_f32 v[42:43], v[42:43], v[78:79], v[50:51]
	v_add_f32_e32 v50, 1.0, v54
	v_rcp_f32_e32 v50, v50
	v_mul_f32_e32 v51, 0xbfb8aa3b, v47
	v_exp_f32_e32 v51, v51
	v_mul_f32_e32 v46, v46, v50
	v_mul_f32_e32 v42, v46, v42
	v_add_f32_e32 v46, 1.0, v51
	v_mul_f32_e32 v50, 0xbfb8aa3b, v48
	v_rcp_f32_e32 v46, v46
	v_exp_f32_e32 v50, v50
	v_mul_f32_e32 v51, 0xbfb8aa3b, v49
	v_exp_f32_e32 v51, v51
	v_mul_f32_e32 v46, v47, v46
	v_add_f32_e32 v47, 1.0, v50
	v_rcp_f32_e32 v47, v47
; __device__ __forceinline__ unsigned cvt_pk_bf16(float lo, float hi) { unsigned r; asm volatile("v_cvt_pk_bf16_f32 %0, %1, %2" : "=v"(r) : "v"(lo), "v"(hi)); return r; }
;     __device__ __forceinline__ void operator()(const f32x4 (&acc)[2][2][4][2], const Unit& u, int wr, int wc, int fr_in, int fq_in) const {
;     ...
;                 for (int bj = 0; bj < 2; ++bj) {
;                     const int tcol = bj * HALF + wc * 32 + 8 * fq + 4 * n;
;                     w0[bj] = *(const f32x4*)(cwl + eo + tcol); w1[bj] = *(const f32x4*)(cwl + eo + 256 + tcol); w2[bj] = *(const f32x4*)(cwl + eo + 512 + tcol); bb[bj] = *(const f32x4*)(cwl + eo + 768 + tcol);
;                     f32x4 E0 = (f32x4){0.f, 0.f, 0.f, 0.f}, E1 = E0;
;                     if (fr < 2) {
;                         if (wr == 1 || ai == 1) {
;                             const int sai = (wr == 1) ? ai : 0, swr = (wr == 1) ? 0 : 1;
;                             const int e = (((((sai * 2 + swr) * 4 + wc) * 2 + bj) * 2 + n) * 4 + fq) * 2;
;                             E0 = ex[e]; E1 = ex[e + 1];
;                         }
;                     }
;                     r1p[bj] = E1; r2p[bj] = (fr == 0) ? E0 : E1;
;     ...
; #pragma unroll
;                 for (int m = 0; m < 4; ++m) {
;                     f32x4 uu[2];
; #pragma unroll
;                     for (int bj = 0; bj < 2; ++bj) {
;                         const f32x4 cur = acc[ai][bj][m][n];
;                         f32x4 r1, r2;
; #pragma unroll
;                         for (int j = 0; j < 4; ++j) { r1[j] = dpp_ror1(cur[j]); r2[j] = dpp_ror2(cur[j]); }
;                         const f32x4 p1 = (fr >= 1) ? r1 : r1p[bj], p2 = (fr >= 2) ? r2 : r2p[bj];
;                         uu[bj] = w0[bj] * p2 + w1[bj] * p1 + w2[bj] * cur + bb[bj];
;                         r1p[bj] = r1; r2p[bj] = r2;
;                     }
;                     const int row = row0 + ai * HALF + m * 16;
;                     float a[4];
; #pragma unroll
;                     for (int j = 0; j < 4; ++j) { const float g = uu[0][j]; a[j] = g * __builtin_amdgcn_rcpf(1.f + __expf(-g)) * uu[1][j]; }
;                     u32x2 w; w.x = cvt_pk_bf16(a[0], a[1]); w.y = cvt_pk_bf16(a[2], a[3]);
;                     *(u32x2*)(ACT + (size_t)row * FFN + u.pn * HALF + wc * 32 + 8 * fq + 4 * n) = w;
	v_add_f32_e32 v50, 1.0, v51
	v_rcp_f32_e32 v50, v50
	v_mul_f32_e32 v43, v46, v43
	v_mul_f32_e32 v46, v48, v47
	v_mul_f32_e32 v44, v46, v44
	v_mul_f32_e32 v46, v49, v50
	v_mul_f32_e32 v45, v46, v45
	v_add_u32_e32 v46, 0xa0, v174
	v_cvt_pk_bf16_f32 v42, v42, v43
	v_cvt_pk_bf16_f32 v43, v44, v45
	v_mad_i64_i32 v[44:45], s[22:23], v46, s25, v[58:59]
	v_lshl_add_u64 v[44:45], v[44:45], 0, s[46:47]
	v_lshl_add_u64 v[44:45], v[44:45], 0, s[62:63]
	v_lshl_add_u64 v[102:103], v[44:45], 0, v[162:163]
	global_store_dwordx2 v[102:103], v[42:43], off
	v_mov_b32_dpp v42, v38 row_ror:1 row_mask:0xf bank_mask:0xf
	v_mov_b32_dpp v48, v38 row_ror:2 row_mask:0xf bank_mask:0xf
	v_mov_b32_dpp v43, v39 row_ror:1 row_mask:0xf bank_mask:0xf
	v_mov_b32_dpp v49, v39 row_ror:2 row_mask:0xf bank_mask:0xf
	v_mov_b32_dpp v44, v40 row_ror:1 row_mask:0xf bank_mask:0xf
	v_mov_b32_dpp v46, v40 row_ror:2 row_mask:0xf bank_mask:0xf
	v_mov_b32_dpp v45, v41 row_ror:1 row_mask:0xf bank_mask:0xf
	v_mov_b32_dpp v47, v41 row_ror:2 row_mask:0xf bank_mask:0xf
	s_nop 0
	v_cndmask_b32_e64 v48, v61, v48, s[42:43]
	v_cndmask_b32_e64 v46, v65, v46, s[42:43]
	v_cndmask_b32_e64 v47, v107, v47, s[42:43]
	v_cndmask_b32_e64 v49, v63, v49, s[42:43]
	v_cndmask_b32_e32 v42, v42, v60, vcc
	v_cndmask_b32_e32 v43, v43, v62, vcc
	v_cndmask_b32_e32 v44, v44, v64, vcc
	v_cndmask_b32_e32 v45, v45, v106, vcc
	v_pk_fma_f32 v[48:49], v[86:87], v[48:49], v[70:71]
	v_pk_fma_f32 v[46:47], v[88:89], v[46:47], v[72:73]
	v_pk_fma_f32 v[42:43], v[82:83], v[42:43], v[48:49]
	v_pk_fma_f32 v[44:45], v[84:85], v[44:45], v[46:47]
	v_pk_fma_f32 v[38:39], v[38:39], v[74:75], v[42:43]
	v_pk_fma_f32 v[40:41], v[40:41], v[76:77], v[44:45]
	v_mov_b32_dpp v42, v34 row_ror:1 row_mask:0xf bank_mask:0xf
	v_mov_b32_dpp v48, v34 row_ror:2 row_mask:0xf bank_mask:0xf
	v_mov_b32_dpp v43, v35 row_ror:1 row_mask:0xf bank_mask:0xf
	v_mov_b32_dpp v49, v35 row_ror:2 row_mask:0xf bank_mask:0xf
	v_mov_b32_dpp v44, v36 row_ror:1 row_mask:0xf bank_mask:0xf
	v_mov_b32_dpp v46, v36 row_ror:2 row_mask:0xf bank_mask:0xf
	v_mov_b32_dpp v45, v37 row_ror:1 row_mask:0xf bank_mask:0xf
	v_mov_b32_dpp v47, v37 row_ror:2 row_mask:0xf bank_mask:0xf
	v_cndmask_b32_e64 v46, v111, v46, s[42:43]
	v_cndmask_b32_e64 v47, v113, v47, s[42:43]
	v_cndmask_b32_e32 v44, v44, v110, vcc
	v_cndmask_b32_e32 v45, v45, v112, vcc
	v_pk_fma_f32 v[46:47], v[96:97], v[46:47], v[68:69]
	v_cndmask_b32_e64 v48, v105, v48, s[42:43]
	v_pk_fma_f32 v[44:45], v[92:93], v[44:45], v[46:47]
	v_mul_f32_e32 v46, 0xbfb8aa3b, v38
	v_exp_f32_e32 v46, v46
	v_cndmask_b32_e64 v49, v109, v49, s[42:43]
	v_cndmask_b32_e32 v42, v42, v104, vcc
	v_cndmask_b32_e32 v43, v43, v108, vcc
	v_pk_fma_f32 v[48:49], v[94:95], v[48:49], v[66:67]
	v_pk_fma_f32 v[42:43], v[90:91], v[42:43], v[48:49]
	v_pk_fma_f32 v[36:37], v[36:37], v[80:81], v[44:45]
	v_pk_fma_f32 v[34:35], v[34:35], v[78:79], v[42:43]
	v_add_f32_e32 v42, 1.0, v46
	v_rcp_f32_e32 v42, v42
	v_mul_f32_e32 v43, 0xbfb8aa3b, v39
	v_exp_f32_e32 v43, v43
	v_mul_f32_e32 v38, v38, v42
	v_mul_f32_e32 v34, v38, v34
	v_add_f32_e32 v38, 1.0, v43
	v_mul_f32_e32 v42, 0xbfb8aa3b, v40
	v_rcp_f32_e32 v38, v38
	v_exp_f32_e32 v42, v42
	v_mul_f32_e32 v43, 0xbfb8aa3b, v41
	v_exp_f32_e32 v43, v43
	v_mul_f32_e32 v38, v39, v38
	v_add_f32_e32 v39, 1.0, v42
	v_rcp_f32_e32 v39, v39
	v_add_f32_e32 v42, 1.0, v43
	v_rcp_f32_e32 v42, v42
	v_mul_f32_e32 v35, v38, v35
	v_mul_f32_e32 v38, v40, v39
	v_mul_f32_e32 v36, v38, v36
	v_mul_f32_e32 v38, v41, v42
	v_mul_f32_e32 v37, v38, v37
	v_add_u32_e32 v38, 0xb0, v174
	v_cvt_pk_bf16_f32 v34, v34, v35
	v_cvt_pk_bf16_f32 v35, v36, v37
	v_mad_i64_i32 v[36:37], s[22:23], v38, s25, v[58:59]
	v_lshl_add_u64 v[36:37], v[36:37], 0, s[46:47]
	v_lshl_add_u64 v[36:37], v[36:37], 0, s[62:63]
	v_lshl_add_u64 v[82:83], v[36:37], 0, v[162:163]
	global_store_dwordx2 v[82:83], v[34:35], off
	ds_read_b128 v[46:49], v214 offset:16
	ds_read_b128 v[42:45], v214 offset:1040
	ds_read_b128 v[38:41], v214 offset:2064
	ds_read_b128 v[34:37], v214 offset:3088
	v_mov_b32_e32 v74, 0
	v_mov_b32_e32 v78, 0
	v_mov_b32_e32 v79, 0
	v_mov_b32_e32 v80, 0
	v_mov_b32_e32 v81, 0
	v_mov_b32_e32 v70, 0
	v_mov_b32_e32 v71, 0
	v_mov_b32_e32 v72, 0
	v_mov_b32_e32 v73, 0
	s_and_saveexec_b64 s[46:47], s[44:45]
	s_cbranch_execz .LBB0_730
	s_lshl_b32 s2, s97, 4
	v_add3_u32 v50, v213, v148, s2
	ds_read_b128 v[78:81], v50
	ds_read_b128 v[70:73], v50 offset:16

; __device__ __forceinline__ unsigned cvt_pk_bf16(float lo, float hi) { unsigned r; asm volatile("v_cvt_pk_bf16_f32 %0, %1, %2" : "=v"(r) : "v"(lo), "v"(hi)); return r; }
; DI float dpp_ror1(float x) { float r; asm volatile("s_nop 1\n\tv_mov_b32_dpp %0, %1 row_ror:1 row_mask:0xf bank_mask:0xf" : "=v"(r) : "v"(x)); return r; }
; DI float dpp_ror2(float x) { float r; asm volatile("s_nop 1\n\tv_mov_b32_dpp %0, %1 row_ror:2 row_mask:0xf bank_mask:0xf" : "=v"(r) : "v"(x)); return r; }
;     __device__ __forceinline__ void operator()(const f32x4 (&acc)[2][2][4][2], const Unit& u, int wr, int wc, int fr_in, int fq_in) const {
;     ...
; #pragma unroll
;                 for (int m = 0; m < 4; ++m) {
;                     f32x4 uu[2];
; #pragma unroll
;                     for (int bj = 0; bj < 2; ++bj) {
;                         const f32x4 cur = acc[ai][bj][m][n];
;                         f32x4 r1, r2;
; #pragma unroll
;                         for (int j = 0; j < 4; ++j) { r1[j] = dpp_ror1(cur[j]); r2[j] = dpp_ror2(cur[j]); }
;                         const f32x4 p1 = (fr >= 1) ? r1 : r1p[bj], p2 = (fr >= 2) ? r2 : r2p[bj];
;                         uu[bj] = w0[bj] * p2 + w1[bj] * p1 + w2[bj] * cur + bb[bj];
;                         r1p[bj] = r1; r2p[bj] = r2;
;                     }
;                     const int row = row0 + ai * HALF + m * 16;
;                     float a[4];
; #pragma unroll
;                     for (int j = 0; j < 4; ++j) { const float g = uu[0][j]; a[j] = g * __builtin_amdgcn_rcpf(1.f + __expf(-g)) * uu[1][j]; }
;                     u32x2 w; w.x = cvt_pk_bf16(a[0], a[1]); w.y = cvt_pk_bf16(a[2], a[3]);
;                     *(u32x2*)(ACT + (size_t)row * FFN + u.pn * HALF + wc * 32 + 8 * fq + 4 * n) = w;
.LBB0_732:
	s_or_b64 exec, exec, s[46:47]
	s_waitcnt lgkmcnt(0)
	v_cndmask_b32_e32 v79, v71, v79, vcc
	v_cndmask_b32_e32 v78, v70, v78, vcc
	v_cndmask_b32_e32 v81, v73, v81, vcc
	v_cndmask_b32_e32 v80, v72, v80, vcc
	v_cndmask_b32_e32 v86, v69, v77, vcc
	v_cndmask_b32_e32 v87, v68, v76, vcc
	v_mov_b32_dpp v88, v30 row_ror:1 row_mask:0xf bank_mask:0xf
	v_mov_b32_dpp v89, v30 row_ror:2 row_mask:0xf bank_mask:0xf
	v_mov_b32_dpp v90, v31 row_ror:1 row_mask:0xf bank_mask:0xf
	v_mov_b32_dpp v91, v31 row_ror:2 row_mask:0xf bank_mask:0xf
	v_cndmask_b32_e32 v84, v67, v75, vcc
	v_cndmask_b32_e64 v76, v78, v89, s[42:43]
	v_cndmask_b32_e64 v77, v79, v91, s[42:43]
	v_cndmask_b32_e32 v85, v66, v74, vcc
	v_mov_b32_dpp v92, v32 row_ror:1 row_mask:0xf bank_mask:0xf
	v_mov_b32_dpp v93, v32 row_ror:2 row_mask:0xf bank_mask:0xf
	v_mov_b32_dpp v94, v33 row_ror:1 row_mask:0xf bank_mask:0xf
	v_mov_b32_dpp v95, v33 row_ror:2 row_mask:0xf bank_mask:0xf
	v_cndmask_b32_e32 v70, v88, v70, vcc
	v_cndmask_b32_e32 v71, v90, v71, vcc
	v_cndmask_b32_e64 v74, v80, v93, s[42:43]
	v_cndmask_b32_e64 v75, v81, v95, s[42:43]
	v_pk_fma_f32 v[76:77], v[46:47], v[76:77], v[34:35]
	v_cndmask_b32_e32 v72, v92, v72, vcc
	v_cndmask_b32_e32 v73, v94, v73, vcc
	v_pk_fma_f32 v[74:75], v[48:49], v[74:75], v[36:37]
	v_pk_fma_f32 v[70:71], v[42:43], v[70:71], v[76:77]
	v_pk_fma_f32 v[72:73], v[44:45], v[72:73], v[74:75]
	v_pk_fma_f32 v[30:31], v[30:31], v[38:39], v[70:71]
	v_mov_b32_dpp v74, v26 row_ror:1 row_mask:0xf bank_mask:0xf
	v_mov_b32_dpp v75, v26 row_ror:2 row_mask:0xf bank_mask:0xf
	v_mov_b32_dpp v76, v27 row_ror:1 row_mask:0xf bank_mask:0xf
	v_mov_b32_dpp v77, v27 row_ror:2 row_mask:0xf bank_mask:0xf
	v_mov_b32_dpp v78, v28 row_ror:1 row_mask:0xf bank_mask:0xf
	v_mov_b32_dpp v79, v28 row_ror:2 row_mask:0xf bank_mask:0xf
	v_mov_b32_dpp v80, v29 row_ror:1 row_mask:0xf bank_mask:0xf
	v_mov_b32_dpp v81, v29 row_ror:2 row_mask:0xf bank_mask:0xf
	s_nop 0
	v_cndmask_b32_e64 v70, v87, v79, s[42:43]
	v_cndmask_b32_e64 v71, v86, v81, s[42:43]
	v_cndmask_b32_e32 v68, v78, v68, vcc
	v_cndmask_b32_e32 v69, v80, v69, vcc
	v_pk_fma_f32 v[70:71], v[64:65], v[70:71], v[52:53]
	v_pk_fma_f32 v[32:33], v[32:33], v[40:41], v[72:73]
	v_pk_fma_f32 v[68:69], v[60:61], v[68:69], v[70:71]
	v_mul_f32_e32 v70, 0xbfb8aa3b, v30
	v_exp_f32_e32 v70, v70
	v_cndmask_b32_e64 v72, v85, v75, s[42:43]
	v_cndmask_b32_e64 v73, v84, v77, s[42:43]
	v_cndmask_b32_e32 v66, v74, v66, vcc
	v_cndmask_b32_e32 v67, v76, v67, vcc
	v_pk_fma_f32 v[72:73], v[62:63], v[72:73], v[50:51]
	v_pk_fma_f32 v[66:67], v[58:59], v[66:67], v[72:73]
	v_pk_fma_f32 v[28:29], v[28:29], v[56:57], v[68:69]
	v_pk_fma_f32 v[26:27], v[26:27], v[54:55], v[66:67]
	v_add_f32_e32 v66, 1.0, v70
	v_rcp_f32_e32 v66, v66
	v_mul_f32_e32 v67, 0xbfb8aa3b, v31
	v_exp_f32_e32 v67, v67
	v_mul_f32_e32 v30, v30, v66
	v_mul_f32_e32 v26, v30, v26
	v_add_f32_e32 v30, 1.0, v67
	v_mul_f32_e32 v66, 0xbfb8aa3b, v32
	v_rcp_f32_e32 v30, v30
	v_exp_f32_e32 v66, v66
	v_mul_f32_e32 v67, 0xbfb8aa3b, v33
	v_exp_f32_e32 v67, v67
	v_mul_f32_e32 v30, v31, v30
	v_add_f32_e32 v31, 1.0, v66
	v_rcp_f32_e32 v31, v31
	v_add_f32_e32 v66, 1.0, v67
	v_rcp_f32_e32 v66, v66
	v_mul_f32_e32 v27, v30, v27
	v_mul_f32_e32 v30, v32, v31
	v_mul_f32_e32 v28, v30, v28
	v_mul_f32_e32 v30, v33, v66
	v_mul_f32_e32 v29, v30, v29
	v_cvt_pk_bf16_f32 v26, v26, v27
	v_cvt_pk_bf16_f32 v27, v28, v29
	global_store_dwordx2 v[98:99], v[26:27], off offset:8
	v_mov_b32_dpp v66, v22 row_ror:1 row_mask:0xf bank_mask:0xf
	v_mov_b32_dpp v67, v22 row_ror:2 row_mask:0xf bank_mask:0xf
	v_mov_b32_dpp v68, v23 row_ror:1 row_mask:0xf bank_mask:0xf
	v_mov_b32_dpp v69, v23 row_ror:2 row_mask:0xf bank_mask:0xf
	v_mov_b32_dpp v70, v24 row_ror:1 row_mask:0xf bank_mask:0xf
	v_mov_b32_dpp v71, v24 row_ror:2 row_mask:0xf bank_mask:0xf
	v_mov_b32_dpp v72, v25 row_ror:1 row_mask:0xf bank_mask:0xf
	s_nop 0
	v_cndmask_b32_e64 v32, v89, v67, s[42:43]
	v_cndmask_b32_e64 v33, v91, v69, s[42:43]
	v_mov_b32_dpp v73, v25 row_ror:2 row_mask:0xf bank_mask:0xf
	v_cndmask_b32_e32 v26, v66, v88, vcc
	v_cndmask_b32_e32 v27, v68, v90, vcc
	v_cndmask_b32_e64 v30, v93, v71, s[42:43]
	v_cndmask_b32_e64 v31, v95, v73, s[42:43]
	v_pk_fma_f32 v[32:33], v[46:47], v[32:33], v[34:35]
	v_cndmask_b32_e32 v28, v70, v92, vcc
	v_cndmask_b32_e32 v29, v72, v94, vcc
	v_pk_fma_f32 v[30:31], v[48:49], v[30:31], v[36:37]
	v_pk_fma_f32 v[26:27], v[42:43], v[26:27], v[32:33]
	v_pk_fma_f32 v[28:29], v[44:45], v[28:29], v[30:31]
	v_pk_fma_f32 v[22:23], v[22:23], v[38:39], v[26:27]
	v_mov_b32_dpp v84, v18 row_ror:1 row_mask:0xf bank_mask:0xf
	v_mov_b32_dpp v85, v18 row_ror:2 row_mask:0xf bank_mask:0xf
	v_mov_b32_dpp v86, v19 row_ror:1 row_mask:0xf bank_mask:0xf
	v_mov_b32_dpp v87, v19 row_ror:2 row_mask:0xf bank_mask:0xf
	v_mov_b32_dpp v88, v20 row_ror:1 row_mask:0xf bank_mask:0xf
	v_mov_b32_dpp v89, v20 row_ror:2 row_mask:0xf bank_mask:0xf
	v_mov_b32_dpp v90, v21 row_ror:1 row_mask:0xf bank_mask:0xf
	v_mov_b32_dpp v91, v21 row_ror:2 row_mask:0xf bank_mask:0xf
	v_pk_fma_f32 v[24:25], v[24:25], v[40:41], v[28:29]
	v_cndmask_b32_e64 v30, v79, v89, s[42:43]
	v_cndmask_b32_e64 v31, v81, v91, s[42:43]
	v_cndmask_b32_e32 v28, v88, v78, vcc
	v_cndmask_b32_e32 v29, v90, v80, vcc
	v_pk_fma_f32 v[30:31], v[64:65], v[30:31], v[52:53]
	v_cndmask_b32_e64 v32, v75, v85, s[42:43]
	v_pk_fma_f32 v[28:29], v[60:61], v[28:29], v[30:31]
	v_mul_f32_e32 v30, 0xbfb8aa3b, v22
	v_exp_f32_e32 v30, v30
	v_cndmask_b32_e64 v33, v77, v87, s[42:43]
	v_cndmask_b32_e32 v26, v84, v74, vcc
	v_cndmask_b32_e32 v27, v86, v76, vcc
	v_pk_fma_f32 v[32:33], v[62:63], v[32:33], v[50:51]
	v_pk_fma_f32 v[26:27], v[58:59], v[26:27], v[32:33]
; __device__ __forceinline__ unsigned cvt_pk_bf16(float lo, float hi) { unsigned r; asm volatile("v_cvt_pk_bf16_f32 %0, %1, %2" : "=v"(r) : "v"(lo), "v"(hi)); return r; }
; DI float dpp_ror1(float x) { float r; asm volatile("s_nop 1\n\tv_mov_b32_dpp %0, %1 row_ror:1 row_mask:0xf bank_mask:0xf" : "=v"(r) : "v"(x)); return r; }
; DI float dpp_ror2(float x) { float r; asm volatile("s_nop 1\n\tv_mov_b32_dpp %0, %1 row_ror:2 row_mask:0xf bank_mask:0xf" : "=v"(r) : "v"(x)); return r; }
;     __device__ __forceinline__ void operator()(const f32x4 (&acc)[2][2][4][2], const Unit& u, int wr, int wc, int fr_in, int fq_in) const {
;     ...
; #pragma unroll
;                 for (int m = 0; m < 4; ++m) {
;                     f32x4 uu[2];
; #pragma unroll
;                     for (int bj = 0; bj < 2; ++bj) {
;                         const f32x4 cur = acc[ai][bj][m][n];
;                         f32x4 r1, r2;
; #pragma unroll
;                         for (int j = 0; j < 4; ++j) { r1[j] = dpp_ror1(cur[j]); r2[j] = dpp_ror2(cur[j]); }
;                         const f32x4 p1 = (fr >= 1) ? r1 : r1p[bj], p2 = (fr >= 2) ? r2 : r2p[bj];
;                         uu[bj] = w0[bj] * p2 + w1[bj] * p1 + w2[bj] * cur + bb[bj];
;                         r1p[bj] = r1; r2p[bj] = r2;
;                     }
;                     const int row = row0 + ai * HALF + m * 16;
;                     float a[4];
; #pragma unroll
;                     for (int j = 0; j < 4; ++j) { const float g = uu[0][j]; a[j] = g * __builtin_amdgcn_rcpf(1.f + __expf(-g)) * uu[1][j]; }
;                     u32x2 w; w.x = cvt_pk_bf16(a[0], a[1]); w.y = cvt_pk_bf16(a[2], a[3]);
;                     *(u32x2*)(ACT + (size_t)row * FFN + u.pn * HALF + wc * 32 + 8 * fq + 4 * n) = w;
	v_pk_fma_f32 v[20:21], v[20:21], v[56:57], v[28:29]
	v_pk_fma_f32 v[18:19], v[18:19], v[54:55], v[26:27]
	v_add_f32_e32 v26, 1.0, v30
	v_rcp_f32_e32 v26, v26
	v_mul_f32_e32 v27, 0xbfb8aa3b, v23
	v_exp_f32_e32 v27, v27
	v_mul_f32_e32 v22, v22, v26
	v_mul_f32_e32 v18, v22, v18
	v_add_f32_e32 v22, 1.0, v27
	v_mul_f32_e32 v26, 0xbfb8aa3b, v24
	v_rcp_f32_e32 v22, v22
	v_exp_f32_e32 v26, v26
	v_mul_f32_e32 v27, 0xbfb8aa3b, v25
	v_exp_f32_e32 v27, v27
	v_mul_f32_e32 v22, v23, v22
	v_add_f32_e32 v23, 1.0, v26
	v_rcp_f32_e32 v23, v23
	v_add_f32_e32 v26, 1.0, v27
	v_rcp_f32_e32 v26, v26
	v_mul_f32_e32 v19, v22, v19
	v_mul_f32_e32 v22, v24, v23
	v_mul_f32_e32 v20, v22, v20
	v_mul_f32_e32 v22, v25, v26
	v_mul_f32_e32 v21, v22, v21
	v_cvt_pk_bf16_f32 v18, v18, v19
	v_cvt_pk_bf16_f32 v19, v20, v21
	global_store_dwordx2 v[100:101], v[18:19], off offset:8
	v_mov_b32_dpp v26, v14 row_ror:1 row_mask:0xf bank_mask:0xf
	v_mov_b32_dpp v27, v14 row_ror:2 row_mask:0xf bank_mask:0xf
	v_mov_b32_dpp v28, v15 row_ror:1 row_mask:0xf bank_mask:0xf
	v_mov_b32_dpp v29, v15 row_ror:2 row_mask:0xf bank_mask:0xf
	v_mov_b32_dpp v30, v16 row_ror:1 row_mask:0xf bank_mask:0xf
	v_mov_b32_dpp v31, v16 row_ror:2 row_mask:0xf bank_mask:0xf
	v_mov_b32_dpp v32, v17 row_ror:1 row_mask:0xf bank_mask:0xf
	s_nop 0
	v_cndmask_b32_e64 v24, v67, v27, s[42:43]
	v_cndmask_b32_e64 v25, v69, v29, s[42:43]
	v_mov_b32_dpp v33, v17 row_ror:2 row_mask:0xf bank_mask:0xf
	v_cndmask_b32_e32 v18, v26, v66, vcc
	v_cndmask_b32_e32 v19, v28, v68, vcc
	v_cndmask_b32_e64 v22, v71, v31, s[42:43]
	v_cndmask_b32_e64 v23, v73, v33, s[42:43]
	v_pk_fma_f32 v[24:25], v[46:47], v[24:25], v[34:35]
	v_cndmask_b32_e32 v20, v30, v70, vcc
	v_cndmask_b32_e32 v21, v32, v72, vcc
	v_pk_fma_f32 v[22:23], v[48:49], v[22:23], v[36:37]
	v_pk_fma_f32 v[18:19], v[42:43], v[18:19], v[24:25]
	v_pk_fma_f32 v[20:21], v[44:45], v[20:21], v[22:23]
	v_pk_fma_f32 v[14:15], v[14:15], v[38:39], v[18:19]
	v_mov_b32_dpp v66, v10 row_ror:1 row_mask:0xf bank_mask:0xf
	v_mov_b32_dpp v67, v10 row_ror:2 row_mask:0xf bank_mask:0xf
	v_mov_b32_dpp v68, v11 row_ror:1 row_mask:0xf bank_mask:0xf
	v_mov_b32_dpp v69, v11 row_ror:2 row_mask:0xf bank_mask:0xf
	v_mov_b32_dpp v70, v12 row_ror:1 row_mask:0xf bank_mask:0xf
	v_mov_b32_dpp v71, v12 row_ror:2 row_mask:0xf bank_mask:0xf
	v_mov_b32_dpp v72, v13 row_ror:1 row_mask:0xf bank_mask:0xf
	v_mov_b32_dpp v73, v13 row_ror:2 row_mask:0xf bank_mask:0xf
	v_pk_fma_f32 v[16:17], v[16:17], v[40:41], v[20:21]
	v_cndmask_b32_e64 v22, v89, v71, s[42:43]
	v_cndmask_b32_e64 v23, v91, v73, s[42:43]
	v_cndmask_b32_e32 v20, v70, v88, vcc
	v_cndmask_b32_e32 v21, v72, v90, vcc
	v_pk_fma_f32 v[22:23], v[64:65], v[22:23], v[52:53]
	v_cndmask_b32_e64 v24, v85, v67, s[42:43]
	v_pk_fma_f32 v[20:21], v[60:61], v[20:21], v[22:23]
	v_mul_f32_e32 v22, 0xbfb8aa3b, v14
	v_exp_f32_e32 v22, v22
	v_cndmask_b32_e64 v25, v87, v69, s[42:43]
	v_cndmask_b32_e32 v18, v66, v84, vcc
	v_cndmask_b32_e32 v19, v68, v86, vcc
	v_pk_fma_f32 v[24:25], v[62:63], v[24:25], v[50:51]
	v_pk_fma_f32 v[18:19], v[58:59], v[18:19], v[24:25]
	v_pk_fma_f32 v[12:13], v[12:13], v[56:57], v[20:21]
	v_pk_fma_f32 v[10:11], v[10:11], v[54:55], v[18:19]
	v_add_f32_e32 v18, 1.0, v22
	v_rcp_f32_e32 v18, v18
	v_mul_f32_e32 v19, 0xbfb8aa3b, v15
	v_exp_f32_e32 v19, v19
	v_mul_f32_e32 v14, v14, v18
	v_mul_f32_e32 v10, v14, v10
	v_add_f32_e32 v14, 1.0, v19
	v_mul_f32_e32 v18, 0xbfb8aa3b, v16
	v_rcp_f32_e32 v14, v14
	v_exp_f32_e32 v18, v18
	v_mul_f32_e32 v19, 0xbfb8aa3b, v17
	v_exp_f32_e32 v19, v19
	v_mul_f32_e32 v14, v15, v14
	v_add_f32_e32 v15, 1.0, v18
	v_rcp_f32_e32 v15, v15
	v_add_f32_e32 v18, 1.0, v19
	v_rcp_f32_e32 v18, v18
	v_mul_f32_e32 v11, v14, v11
	v_mul_f32_e32 v14, v16, v15
	v_mul_f32_e32 v12, v14, v12
	v_mul_f32_e32 v14, v17, v18
	v_mul_f32_e32 v13, v14, v13
	v_cvt_pk_bf16_f32 v10, v10, v11
	v_cvt_pk_bf16_f32 v11, v12, v13
	global_store_dwordx2 v[102:103], v[10:11], off offset:8
	v_mov_b32_dpp v12, v6 row_ror:1 row_mask:0xf bank_mask:0xf
	v_mov_b32_dpp v14, v6 row_ror:2 row_mask:0xf bank_mask:0xf
	v_mov_b32_dpp v13, v7 row_ror:1 row_mask:0xf bank_mask:0xf
	v_mov_b32_dpp v15, v7 row_ror:2 row_mask:0xf bank_mask:0xf
	v_mov_b32_dpp v10, v8 row_ror:1 row_mask:0xf bank_mask:0xf
	v_mov_b32_dpp v16, v8 row_ror:2 row_mask:0xf bank_mask:0xf
	s_nop 0
	v_cndmask_b32_e32 v12, v12, v26, vcc
	v_cndmask_b32_e64 v14, v27, v14, s[42:43]
	v_cndmask_b32_e64 v15, v29, v15, s[42:43]
	v_cndmask_b32_e32 v13, v13, v28, vcc
	v_pk_fma_f32 v[14:15], v[46:47], v[14:15], v[34:35]
	v_mov_b32_dpp v11, v9 row_ror:1 row_mask:0xf bank_mask:0xf
	v_mov_b32_dpp v17, v9 row_ror:2 row_mask:0xf bank_mask:0xf
	v_cndmask_b32_e64 v16, v31, v16, s[42:43]
	v_pk_fma_f32 v[12:13], v[42:43], v[12:13], v[14:15]
	v_cndmask_b32_e64 v17, v33, v17, s[42:43]
	v_pk_fma_f32 v[6:7], v[6:7], v[38:39], v[12:13]
	v_cndmask_b32_e32 v10, v10, v30, vcc
	v_cndmask_b32_e32 v11, v11, v32, vcc
	v_mul_f32_e32 v14, 0xbfb8aa3b, v6
	v_mov_b32_dpp v18, v2 row_ror:1 row_mask:0xf bank_mask:0xf
	v_mov_b32_dpp v24, v2 row_ror:2 row_mask:0xf bank_mask:0xf
	v_mov_b32_dpp v19, v3 row_ror:1 row_mask:0xf bank_mask:0xf
	v_mov_b32_dpp v25, v3 row_ror:2 row_mask:0xf bank_mask:0xf
	v_pk_fma_f32 v[16:17], v[48:49], v[16:17], v[36:37]
	v_exp_f32_e32 v14, v14
	v_cndmask_b32_e64 v24, v67, v24, s[42:43]
	v_cndmask_b32_e64 v25, v69, v25, s[42:43]
	v_pk_fma_f32 v[10:11], v[44:45], v[10:11], v[16:17]
	v_cndmask_b32_e32 v18, v18, v66, vcc
	v_cndmask_b32_e32 v19, v19, v68, vcc
	v_pk_fma_f32 v[8:9], v[8:9], v[40:41], v[10:11]
	v_pk_fma_f32 v[10:11], v[62:63], v[24:25], v[50:51]
	v_pk_fma_f32 v[10:11], v[58:59], v[18:19], v[10:11]
	v_mov_b32_dpp v20, v4 row_ror:1 row_mask:0xf bank_mask:0xf
	v_mov_b32_dpp v22, v4 row_ror:2 row_mask:0xf bank_mask:0xf
	v_mov_b32_dpp v21, v5 row_ror:1 row_mask:0xf bank_mask:0xf
	v_mov_b32_dpp v23, v5 row_ror:2 row_mask:0xf bank_mask:0xf
	s_nop 0
	v_pk_fma_f32 v[2:3], v[2:3], v[54:55], v[10:11]
	v_add_f32_e32 v10, 1.0, v14
	v_rcp_f32_e32 v10, v10
	v_mul_f32_e32 v11, 0xbfb8aa3b, v7
	v_exp_f32_e32 v11, v11
	v_mul_f32_e32 v6, v6, v10
	v_mul_f32_e32 v2, v6, v2
	v_add_f32_e32 v6, 1.0, v11
	v_mul_f32_e32 v10, 0xbfb8aa3b, v8
	v_rcp_f32_e32 v6, v6
	v_exp_f32_e32 v10, v10
	v_mul_f32_e32 v11, 0xbfb8aa3b, v9
	v_exp_f32_e32 v11, v11
	v_mul_f32_e32 v6, v7, v6
	v_add_f32_e32 v7, 1.0, v10
	v_cndmask_b32_e64 v22, v71, v22, s[42:43]
	v_cndmask_b32_e64 v23, v73, v23, s[42:43]
	v_rcp_f32_e32 v7, v7
	v_add_f32_e32 v10, 1.0, v11
	v_cndmask_b32_e32 v20, v20, v70, vcc
	v_cndmask_b32_e32 v21, v21, v72, vcc
	v_pk_fma_f32 v[12:13], v[64:65], v[22:23], v[52:53]
	v_rcp_f32_e32 v10, v10
	v_pk_fma_f32 v[12:13], v[60:61], v[20:21], v[12:13]
	v_mul_f32_e32 v3, v6, v3
	v_pk_fma_f32 v[4:5], v[4:5], v[56:57], v[12:13]
	v_mul_f32_e32 v6, v8, v7
	s_andn2_b64 vcc, exec, s[40:41]
	v_mul_f32_e32 v4, v6, v4
	v_mul_f32_e32 v6, v9, v10
	s_mov_b64 s[40:41], -1
	v_mul_f32_e32 v5, v6, v5
	v_cvt_pk_bf16_f32 v2, v2, v3
	v_cvt_pk_bf16_f32 v3, v4, v5
	global_store_dwordx2 v[82:83], v[2:3], off offset:8
	s_cbranch_vccnz .LBB0_701
; #define PG8_LAS __attribute__((address_space(3)))
; #define PG8_BAR __builtin_amdgcn_s_barrier()
; DI int opaque_lane() { int l; asm volatile("v_mbcnt_lo_u32_b32 %0, -1, 0\n\tv_mbcnt_hi_u32_b32 %0, -1, %0" : "=v"(l)); return l; }
; template <class Epi, class Sched, bool ALIGN_EPI = false, bool SP2 = false>
; __device__ __forceinline__ void gemm_phase(PG8_LAS unsigned char* lds, const Gemm g, const Sched& S, const Epi& E, const int wid_in) {
;     ...
;         if constexpr (ALIGN_EPI) { if (wr == 1) PG8_BAR; }
;     __device__ __forceinline__ void pre(const Unit& u, int wr, int wc) const {
;         const int lane_p = opaque_lane(); const int wv = wr * 4 + wc, t = wv * 64 + lane_p;
;         PG8_LAS unsigned char* dst = cwl3 + par_w * 6144 + wv * 256;
; #pragma unroll
;         for (int i = 0; i < 2; ++i) { const int idx = t + 512 * i, k = idx >> 8, c = idx & 255;
;             const int oc = (c < 128) ? (u.pn * HALF + c) : (FFN + u.pn * HALF + c - 128);
;             const float* src = (k < 3) ? (cw + (size_t)k * NUP + oc) : (cb + oc);
;             __builtin_amdgcn_global_load_lds((const unsigned*)src, (PG8_LAS unsigned*)(dst + i * 2048), 4, 0, 0); }
;         par_w ^= 1;
;     }
	v_readlane_b32 s2, v243, 48
	v_mbcnt_lo_u32_b32 v2, -1, 0
	v_mbcnt_hi_u32_b32 v2, -1, v2
	v_mov_b64_e32 v[4:5], s[56:57]
	s_nop 0
	v_add_u32_e32 v6, s2, v2
	v_ashrrev_i32_e32 v2, 8, v6
	v_cmp_gt_i32_e32 vcc, 3, v2
	s_and_saveexec_b64 s[40:41], vcc
	v_mul_hi_i32_i24_e32 v3, 0x5800, v2
	v_mul_i32_i24_e32 v2, 0x5800, v2
	v_lshl_add_u64 v[4:5], s[54:55], 0, v[2:3]
	s_or_b64 exec, exec, s[40:41]
	s_lshl_b32 s8, s58, 7
	v_or_b32_sdwa v2, v6, s8 dst_sel:DWORD dst_unused:UNUSED_PAD src0_sel:BYTE_0 src1_sel:DWORD
	s_addk_i32 s8, 0xa80
	v_add_u32_sdwa v3, s8, v6 dst_sel:DWORD dst_unused:UNUSED_PAD src0_sel:DWORD src1_sel:BYTE_0
	s_movk_i32 s8, 0x80
	v_cmp_lt_u32_sdwa vcc, v6, s8 src0_sel:BYTE_0 src1_sel:DWORD
	s_mul_i32 s2, s4, 0x1800
	v_readlane_b32 s8, v239, 22
	v_cndmask_b32_e32 v2, v3, v2, vcc
	v_ashrrev_i32_e32 v3, 31, v2
	s_add_i32 s2, s8, s2
	v_lshl_add_u64 v[4:5], v[2:3], 2, v[4:5]
	s_mov_b32 m0, s2
	s_nop 0
	global_load_lds_dword v[4:5], off
	v_add_u32_e32 v4, 0x200, v6
	v_ashrrev_i32_e32 v6, 8, v4
	v_cmp_gt_i32_e32 vcc, 3, v6
	v_mov_b64_e32 v[4:5], s[56:57]
	s_and_saveexec_b64 s[40:41], vcc
	v_mul_hi_i32_i24_e32 v5, 0x5800, v6
	v_mul_i32_i24_e32 v4, 0x5800, v6
	v_lshl_add_u64 v[4:5], s[54:55], 0, v[4:5]
	s_or_b64 exec, exec, s[40:41]
	v_lshl_add_u64 v[2:3], v[2:3], 2, v[4:5]
	s_add_i32 m0, s2, 0x800
	v_readlane_b32 s8, v239, 42
	global_load_lds_dword v[2:3], off
	v_readlane_b32 s9, v239, 43
	s_and_b64 vcc, exec, s[8:9]
	s_cbranch_vccnz .LBB0_700
	s_barrier
	s_branch .LBB0_700
